# GEMM compute segments: removed the adjacent s_setprio 0 / s_setprio 1 pair between the two 16-MFMA blocks (priority stays raised across both)
# speedup vs baseline: 1.0076x; 1.0076x over previous
.LBB0_121:
	ds_read_b128 v[166:169], v163
	ds_read_b128 v[170:173], v163 offset:1024
	ds_read_b128 v[174:177], v163 offset:2048
	ds_read_b128 v[178:181], v163 offset:3072
	ds_read_b128 v[182:185], v164
	ds_read_b128 v[186:189], v164 offset:1024
	ds_read_b128 v[190:193], v164 offset:2048
	ds_read_b128 v[194:197], v164 offset:3072
	s_add_u32 s28, s26, 0xfff80080
	s_addc_u32 s29, s27, -1
	s_cmp_eq_u32 s57, 28
	s_cselect_b32 s31, s19, s29
	s_cselect_b32 s30, s53, s28
	s_cselect_b32 s29, s17, s56
	s_cselect_b32 s28, s54, s55
	v_lshl_add_u64 v[144:145], s[26:27], 0, v[136:137]
	s_add_i32 m0, s25, 0xc000
	ds_read_b128 v[198:201], v165
	ds_read_b128 v[202:205], v165 offset:1024
	ds_read_b128 v[206:209], v165 offset:2048
	ds_read_b128 v[214:217], v165 offset:3072
	ds_read_b128 v[218:221], v165 offset:4096
	ds_read_b128 v[222:225], v165 offset:5120
	ds_read_b128 v[226:229], v165 offset:6144
	ds_read_b128 v[230:233], v165 offset:7168
	global_load_lds_dwordx4 v[144:145], off
	v_lshl_add_u64 v[144:145], s[26:27], 0, v[138:139]
	s_add_i32 m0, s25, 0xe000
	s_nop 0
	global_load_lds_dwordx4 v[144:145], off
	s_waitcnt vmcnt(8)
	s_waitcnt lgkmcnt(0)
	s_barrier
	s_setprio 1
	s_waitcnt lgkmcnt(0)
	v_mfma_f32_16x16x32_bf16 v[124:127], v[166:169], v[198:201], v[124:127]
	v_mfma_f32_16x16x32_bf16 v[120:123], v[174:177], v[198:201], v[120:123]
	v_mfma_f32_16x16x32_bf16 v[108:111], v[166:169], v[206:209], v[108:111]
	v_mfma_f32_16x16x32_bf16 v[104:107], v[174:177], v[206:209], v[104:107]
	v_mfma_f32_16x16x32_bf16 v[92:95], v[166:169], v[218:221], v[92:95]
	v_mfma_f32_16x16x32_bf16 v[88:91], v[174:177], v[218:221], v[88:91]
	v_mfma_f32_16x16x32_bf16 v[76:79], v[166:169], v[226:229], v[76:79]
	v_mfma_f32_16x16x32_bf16 v[72:75], v[174:177], v[226:229], v[72:75]
	v_mfma_f32_16x16x32_bf16 v[124:127], v[170:173], v[202:205], v[124:127]
	v_mfma_f32_16x16x32_bf16 v[120:123], v[178:181], v[202:205], v[120:123]
	v_mfma_f32_16x16x32_bf16 v[108:111], v[170:173], v[214:217], v[108:111]
	v_mfma_f32_16x16x32_bf16 v[104:107], v[178:181], v[214:217], v[104:107]
	v_mfma_f32_16x16x32_bf16 v[92:95], v[170:173], v[222:225], v[92:95]
	v_mfma_f32_16x16x32_bf16 v[88:91], v[178:181], v[222:225], v[88:91]
	v_mfma_f32_16x16x32_bf16 v[76:79], v[170:173], v[230:233], v[76:79]
	v_mfma_f32_16x16x32_bf16 v[72:75], v[178:181], v[230:233], v[72:75]
	v_mfma_f32_16x16x32_bf16 v[116:119], v[182:185], v[198:201], v[116:119]
	v_mfma_f32_16x16x32_bf16 v[112:115], v[190:193], v[198:201], v[112:115]
	v_mfma_f32_16x16x32_bf16 v[100:103], v[182:185], v[206:209], v[100:103]
	v_mfma_f32_16x16x32_bf16 v[96:99], v[190:193], v[206:209], v[96:99]
	v_mfma_f32_16x16x32_bf16 v[84:87], v[182:185], v[218:221], v[84:87]
	v_mfma_f32_16x16x32_bf16 v[80:83], v[190:193], v[218:221], v[80:83]
	v_mfma_f32_16x16x32_bf16 v[68:71], v[182:185], v[226:229], v[68:71]
	v_mfma_f32_16x16x32_bf16 v[64:67], v[190:193], v[226:229], v[64:67]
	v_mfma_f32_16x16x32_bf16 v[116:119], v[186:189], v[202:205], v[116:119]
	v_mfma_f32_16x16x32_bf16 v[112:115], v[194:197], v[202:205], v[112:115]
	v_mfma_f32_16x16x32_bf16 v[100:103], v[186:189], v[214:217], v[100:103]
	v_mfma_f32_16x16x32_bf16 v[96:99], v[194:197], v[214:217], v[96:99]
	v_mfma_f32_16x16x32_bf16 v[84:87], v[186:189], v[222:225], v[84:87]
	v_mfma_f32_16x16x32_bf16 v[80:83], v[194:197], v[222:225], v[80:83]
	v_mfma_f32_16x16x32_bf16 v[68:71], v[186:189], v[230:233], v[68:71]
	v_mfma_f32_16x16x32_bf16 v[64:67], v[194:197], v[230:233], v[64:67]
	s_setprio 0
	s_barrier
	s_add_i32 s58, s49, s42
	v_lshl_add_u64 v[144:145], s[28:29], 0, v[132:133]
	s_mov_b32 m0, s58
	ds_read_b128 v[198:201], v165 offset:16384
	ds_read_b128 v[202:205], v165 offset:17408
	ds_read_b128 v[206:209], v165 offset:18432
	ds_read_b128 v[214:217], v165 offset:19456
	ds_read_b128 v[218:221], v165 offset:20480
	ds_read_b128 v[222:225], v165 offset:21504
	ds_read_b128 v[226:229], v165 offset:22528
	ds_read_b128 v[230:233], v165 offset:23552
	global_load_lds_dwordx4 v[144:145], off
	s_add_i32 m0, s58, 0x2000
	s_add_u32 s58, s28, 0x80000
	v_lshl_add_u64 v[210:211], s[28:29], 0, v[128:129]
	s_addc_u32 s59, s29, 0
	s_add_i32 s60, s50, s42
	global_load_lds_dwordx4 v[210:211], off
	v_lshl_add_u64 v[234:235], s[58:59], 0, v[132:133]
	s_mov_b32 m0, s60
	v_lshl_add_u64 v[236:237], s[30:31], 0, v[130:131]
	global_load_lds_dwordx4 v[234:235], off
	v_lshl_add_u64 v[234:235], s[58:59], 0, v[128:129]
	s_add_i32 m0, s60, 0x2000
	s_nop 0
	global_load_lds_dwordx4 v[234:235], off
	v_lshl_add_u64 v[234:235], s[30:31], 0, v[134:135]
	s_mov_b32 m0, s25
	s_nop 0
	global_load_lds_dwordx4 v[234:235], off
	s_mov_b32 m0, s44
	s_nop 0
	global_load_lds_dwordx4 v[236:237], off
	s_waitcnt vmcnt(8)
	s_waitcnt lgkmcnt(0)
	s_barrier
	s_setprio 1
	s_waitcnt lgkmcnt(0)
	v_mfma_f32_16x16x32_bf16 v[60:63], v[166:169], v[198:201], v[60:63]
	v_mfma_f32_16x16x32_bf16 v[56:59], v[174:177], v[198:201], v[56:59]
	v_mfma_f32_16x16x32_bf16 v[44:47], v[166:169], v[206:209], v[44:47]
	v_mfma_f32_16x16x32_bf16 v[40:43], v[174:177], v[206:209], v[40:43]
	v_mfma_f32_16x16x32_bf16 v[28:31], v[166:169], v[218:221], v[28:31]
	v_mfma_f32_16x16x32_bf16 v[24:27], v[174:177], v[218:221], v[24:27]
	v_mfma_f32_16x16x32_bf16 v[12:15], v[166:169], v[226:229], v[12:15]
	v_mfma_f32_16x16x32_bf16 v[8:11], v[174:177], v[226:229], v[8:11]
	v_mfma_f32_16x16x32_bf16 v[60:63], v[170:173], v[202:205], v[60:63]
	v_mfma_f32_16x16x32_bf16 v[56:59], v[178:181], v[202:205], v[56:59]
	v_mfma_f32_16x16x32_bf16 v[44:47], v[170:173], v[214:217], v[44:47]
	v_mfma_f32_16x16x32_bf16 v[40:43], v[178:181], v[214:217], v[40:43]
	v_mfma_f32_16x16x32_bf16 v[28:31], v[170:173], v[222:225], v[28:31]
	v_mfma_f32_16x16x32_bf16 v[24:27], v[178:181], v[222:225], v[24:27]
	v_mfma_f32_16x16x32_bf16 v[12:15], v[170:173], v[230:233], v[12:15]
	v_mfma_f32_16x16x32_bf16 v[8:11], v[178:181], v[230:233], v[8:11]
	v_mfma_f32_16x16x32_bf16 v[52:55], v[182:185], v[198:201], v[52:55]
	v_mfma_f32_16x16x32_bf16 v[48:51], v[190:193], v[198:201], v[48:51]
	v_mfma_f32_16x16x32_bf16 v[36:39], v[182:185], v[206:209], v[36:39]
	v_mfma_f32_16x16x32_bf16 v[32:35], v[190:193], v[206:209], v[32:35]
	v_mfma_f32_16x16x32_bf16 v[20:23], v[182:185], v[218:221], v[20:23]
	v_mfma_f32_16x16x32_bf16 v[16:19], v[190:193], v[218:221], v[16:19]
	v_mfma_f32_16x16x32_bf16 v[4:7], v[182:185], v[226:229], v[4:7]
	v_mfma_f32_16x16x32_bf16 v[0:3], v[190:193], v[226:229], v[0:3]
	v_mfma_f32_16x16x32_bf16 v[52:55], v[186:189], v[202:205], v[52:55]
	v_mfma_f32_16x16x32_bf16 v[48:51], v[194:197], v[202:205], v[48:51]
	v_mfma_f32_16x16x32_bf16 v[36:39], v[186:189], v[214:217], v[36:39]
	v_mfma_f32_16x16x32_bf16 v[32:35], v[194:197], v[214:217], v[32:35]
	v_mfma_f32_16x16x32_bf16 v[20:23], v[186:189], v[222:225], v[20:23]
	v_mfma_f32_16x16x32_bf16 v[16:19], v[194:197], v[222:225], v[16:19]
	v_mfma_f32_16x16x32_bf16 v[4:7], v[186:189], v[230:233], v[4:7]
	v_mfma_f32_16x16x32_bf16 v[0:3], v[194:197], v[230:233], v[0:3]
	s_setprio 0
	s_barrier
	s_add_i32 s58, 0, 0x18000
	s_add_i32 s59, 0, 0x1c000
	v_add_u32_e32 v178, s58, v161
	v_add_u32_e32 v194, s59, v161
	ds_read_b128 v[166:169], v178
	ds_read_b128 v[170:173], v178 offset:1024
	ds_read_b128 v[174:177], v178 offset:2048
	ds_read_b128 v[178:181], v178 offset:3072
	ds_read_b128 v[182:185], v194
	ds_read_b128 v[186:189], v194 offset:1024
	ds_read_b128 v[190:193], v194 offset:2048
	ds_read_b128 v[194:197], v194 offset:3072
	s_add_u32 s30, s30, 0x80000
	s_addc_u32 s31, s31, 0
	s_mov_b32 m0, s45
	v_lshl_add_u64 v[238:239], s[30:31], 0, v[134:135]
	ds_read_b128 v[198:201], v165 offset:32768
	ds_read_b128 v[202:205], v165 offset:33792
	ds_read_b128 v[206:209], v165 offset:34816
	ds_read_b128 v[214:217], v165 offset:35840
	ds_read_b128 v[218:221], v165 offset:36864
	ds_read_b128 v[222:225], v165 offset:37888
	ds_read_b128 v[226:229], v165 offset:38912
	ds_read_b128 v[230:233], v165 offset:39936
	global_load_lds_dwordx4 v[238:239], off
	v_lshl_add_u64 v[238:239], s[30:31], 0, v[130:131]
	s_mov_b32 m0, s46
	s_nop 0
	global_load_lds_dwordx4 v[238:239], off
	s_waitcnt vmcnt(8)
	s_waitcnt lgkmcnt(0)
	s_barrier
	s_setprio 1
	s_waitcnt lgkmcnt(0)
	v_mfma_f32_16x16x32_bf16 v[124:127], v[166:169], v[198:201], v[124:127]
	v_mfma_f32_16x16x32_bf16 v[120:123], v[174:177], v[198:201], v[120:123]
	v_mfma_f32_16x16x32_bf16 v[108:111], v[166:169], v[206:209], v[108:111]
	v_mfma_f32_16x16x32_bf16 v[104:107], v[174:177], v[206:209], v[104:107]
	v_mfma_f32_16x16x32_bf16 v[92:95], v[166:169], v[218:221], v[92:95]
	v_mfma_f32_16x16x32_bf16 v[88:91], v[174:177], v[218:221], v[88:91]
	v_mfma_f32_16x16x32_bf16 v[76:79], v[166:169], v[226:229], v[76:79]
	v_mfma_f32_16x16x32_bf16 v[72:75], v[174:177], v[226:229], v[72:75]
	v_mfma_f32_16x16x32_bf16 v[124:127], v[170:173], v[202:205], v[124:127]
	v_mfma_f32_16x16x32_bf16 v[120:123], v[178:181], v[202:205], v[120:123]
	v_mfma_f32_16x16x32_bf16 v[108:111], v[170:173], v[214:217], v[108:111]
	v_mfma_f32_16x16x32_bf16 v[104:107], v[178:181], v[214:217], v[104:107]
	v_mfma_f32_16x16x32_bf16 v[92:95], v[170:173], v[222:225], v[92:95]
	v_mfma_f32_16x16x32_bf16 v[88:91], v[178:181], v[222:225], v[88:91]
	v_mfma_f32_16x16x32_bf16 v[76:79], v[170:173], v[230:233], v[76:79]
	v_mfma_f32_16x16x32_bf16 v[72:75], v[178:181], v[230:233], v[72:75]
	v_mfma_f32_16x16x32_bf16 v[116:119], v[182:185], v[198:201], v[116:119]
	v_mfma_f32_16x16x32_bf16 v[112:115], v[190:193], v[198:201], v[112:115]
	v_mfma_f32_16x16x32_bf16 v[100:103], v[182:185], v[206:209], v[100:103]
	v_mfma_f32_16x16x32_bf16 v[96:99], v[190:193], v[206:209], v[96:99]
	v_mfma_f32_16x16x32_bf16 v[84:87], v[182:185], v[218:221], v[84:87]
	v_mfma_f32_16x16x32_bf16 v[80:83], v[190:193], v[218:221], v[80:83]
	v_mfma_f32_16x16x32_bf16 v[68:71], v[182:185], v[226:229], v[68:71]
	v_mfma_f32_16x16x32_bf16 v[64:67], v[190:193], v[226:229], v[64:67]
	v_mfma_f32_16x16x32_bf16 v[116:119], v[186:189], v[202:205], v[116:119]
	v_mfma_f32_16x16x32_bf16 v[112:115], v[194:197], v[202:205], v[112:115]
	v_mfma_f32_16x16x32_bf16 v[100:103], v[186:189], v[214:217], v[100:103]
	v_mfma_f32_16x16x32_bf16 v[96:99], v[194:197], v[214:217], v[96:99]
	v_mfma_f32_16x16x32_bf16 v[84:87], v[186:189], v[222:225], v[84:87]
	v_mfma_f32_16x16x32_bf16 v[80:83], v[194:197], v[222:225], v[80:83]
	v_mfma_f32_16x16x32_bf16 v[68:71], v[186:189], v[230:233], v[68:71]
	v_mfma_f32_16x16x32_bf16 v[64:67], v[194:197], v[230:233], v[64:67]
	s_setprio 0
	s_barrier
	s_add_i32 s30, s58, s42
	v_lshl_add_u64 v[144:145], v[144:145], 0, s[12:13]
	s_mov_b32 m0, s30
	ds_read_b128 v[198:201], v165 offset:49152
	ds_read_b128 v[202:205], v165 offset:50176
	ds_read_b128 v[206:209], v165 offset:51200
	ds_read_b128 v[214:217], v165 offset:52224
	ds_read_b128 v[218:221], v165 offset:53248
	ds_read_b128 v[222:225], v165 offset:54272
	ds_read_b128 v[226:229], v165 offset:55296
	ds_read_b128 v[230:233], v165 offset:56320
	global_load_lds_dwordx4 v[144:145], off
	s_add_i32 m0, s30, 0x2000
	s_add_u32 s28, s28, 0x80080
	v_lshl_add_u64 v[144:145], v[210:211], 0, s[12:13]
	s_addc_u32 s29, s29, 0
	s_add_i32 s30, s59, s42
	global_load_lds_dwordx4 v[144:145], off
	v_lshl_add_u64 v[144:145], s[28:29], 0, v[132:133]
	s_mov_b32 m0, s30
	s_nop 0
	global_load_lds_dwordx4 v[144:145], off
	v_lshl_add_u64 v[144:145], s[28:29], 0, v[128:129]
	s_add_i32 m0, s30, 0x2000
	s_nop 0
	global_load_lds_dwordx4 v[144:145], off
	v_lshl_add_u64 v[144:145], v[234:235], 0, s[12:13]
	s_mov_b32 m0, s33
	s_nop 0
	global_load_lds_dwordx4 v[144:145], off
	v_lshl_add_u64 v[144:145], v[236:237], 0, s[12:13]
	s_mov_b32 m0, s48
	s_nop 0
	global_load_lds_dwordx4 v[144:145], off
	s_waitcnt vmcnt(8)
	s_waitcnt lgkmcnt(0)
	s_barrier
	s_setprio 1
	s_waitcnt lgkmcnt(0)
	v_mfma_f32_16x16x32_bf16 v[60:63], v[166:169], v[198:201], v[60:63]
	v_mfma_f32_16x16x32_bf16 v[56:59], v[174:177], v[198:201], v[56:59]
	v_mfma_f32_16x16x32_bf16 v[44:47], v[166:169], v[206:209], v[44:47]
	v_mfma_f32_16x16x32_bf16 v[40:43], v[174:177], v[206:209], v[40:43]
	v_mfma_f32_16x16x32_bf16 v[28:31], v[166:169], v[218:221], v[28:31]
	v_mfma_f32_16x16x32_bf16 v[24:27], v[174:177], v[218:221], v[24:27]
	v_mfma_f32_16x16x32_bf16 v[12:15], v[166:169], v[226:229], v[12:15]
	v_mfma_f32_16x16x32_bf16 v[8:11], v[174:177], v[226:229], v[8:11]
	v_mfma_f32_16x16x32_bf16 v[60:63], v[170:173], v[202:205], v[60:63]
	v_mfma_f32_16x16x32_bf16 v[56:59], v[178:181], v[202:205], v[56:59]
	v_mfma_f32_16x16x32_bf16 v[44:47], v[170:173], v[214:217], v[44:47]
	v_mfma_f32_16x16x32_bf16 v[40:43], v[178:181], v[214:217], v[40:43]
	v_mfma_f32_16x16x32_bf16 v[28:31], v[170:173], v[222:225], v[28:31]
	v_mfma_f32_16x16x32_bf16 v[24:27], v[178:181], v[222:225], v[24:27]
	v_mfma_f32_16x16x32_bf16 v[12:15], v[170:173], v[230:233], v[12:15]
	v_mfma_f32_16x16x32_bf16 v[8:11], v[178:181], v[230:233], v[8:11]
	v_mfma_f32_16x16x32_bf16 v[52:55], v[182:185], v[198:201], v[52:55]
	v_mfma_f32_16x16x32_bf16 v[48:51], v[190:193], v[198:201], v[48:51]
	v_mfma_f32_16x16x32_bf16 v[36:39], v[182:185], v[206:209], v[36:39]
	v_mfma_f32_16x16x32_bf16 v[32:35], v[190:193], v[206:209], v[32:35]
	v_mfma_f32_16x16x32_bf16 v[20:23], v[182:185], v[218:221], v[20:23]
	v_mfma_f32_16x16x32_bf16 v[16:19], v[190:193], v[218:221], v[16:19]
	v_mfma_f32_16x16x32_bf16 v[4:7], v[182:185], v[226:229], v[4:7]
	v_mfma_f32_16x16x32_bf16 v[0:3], v[190:193], v[226:229], v[0:3]
	v_mfma_f32_16x16x32_bf16 v[52:55], v[186:189], v[202:205], v[52:55]
	v_mfma_f32_16x16x32_bf16 v[48:51], v[194:197], v[202:205], v[48:51]
	v_mfma_f32_16x16x32_bf16 v[36:39], v[186:189], v[214:217], v[36:39]
	v_mfma_f32_16x16x32_bf16 v[32:35], v[194:197], v[214:217], v[32:35]
	v_mfma_f32_16x16x32_bf16 v[20:23], v[186:189], v[222:225], v[20:23]
	v_mfma_f32_16x16x32_bf16 v[16:19], v[194:197], v[222:225], v[16:19]
	v_mfma_f32_16x16x32_bf16 v[4:7], v[186:189], v[230:233], v[4:7]
	v_mfma_f32_16x16x32_bf16 v[0:3], v[194:197], v[230:233], v[0:3]
	s_setprio 0
	s_barrier
	s_add_i32 s57, s57, 2
	s_add_u32 s26, s26, 0x100
	s_addc_u32 s27, s27, 0
	s_add_u32 s55, s55, 0x100
	s_addc_u32 s56, s56, 0
	s_cmp_gt_u32 s57, 29
	s_cbranch_scc0 .LBB0_121
	s_and_b64 vcc, exec, s[14:15]
	s_cbranch_vccz .LBB0_124
	s_barrier

.LBB0_144:
	s_add_u32 s53, s46, s52
	s_addc_u32 s58, s47, 0
	s_add_u32 s56, s53, 0x100
	s_addc_u32 s57, s58, 0
	s_and_b64 s[54:55], s[50:51], exec
	s_cselect_b32 s55, s39, s57
	s_cselect_b32 s54, s81, s56
	s_add_u32 s52, s44, s52
	s_addc_u32 s56, s45, 0
	s_add_u32 s52, s52, 0x100
	s_addc_u32 s56, s56, 0
	s_add_i32 s91, 0, 0x10000
	s_and_b64 s[50:51], s[50:51], exec
	s_cselect_b32 s57, s37, s56
	s_cselect_b32 s56, s82, s52
	s_add_i32 s51, 0, 0x14000
	s_add_u32 s60, s53, 0x10080
	s_addc_u32 s61, s58, 0
	s_add_i32 s90, s91, s71
	s_add_i32 m0, s72, 0xc000
	s_add_i32 s93, s72, 0xe000
	s_add_i32 s87, s90, 0x2000
	v_add_u32_e32 v140, s91, v151
	s_add_u32 s58, s56, 0x10000
	ds_read_b128 v[154:157], v140
	ds_read_b128 v[158:161], v140 offset:1024
	ds_read_b128 v[162:165], v140 offset:2048
	ds_read_b128 v[166:169], v140 offset:3072
	v_add_u32_e32 v140, s51, v151
	s_addc_u32 s59, s57, 0
	s_add_i32 s89, s51, s71
	ds_read_b128 v[170:173], v140
	ds_read_b128 v[174:177], v140 offset:1024
	ds_read_b128 v[178:181], v140 offset:2048
	ds_read_b128 v[182:185], v140 offset:3072
	s_add_i32 s88, s89, 0x2000
	s_add_i32 s86, 0, 0x18000
	s_add_i32 s85, 0, 0x1c000
	s_add_u32 s52, s54, 0x10000
	s_addc_u32 s53, s55, 0
	s_add_i32 s84, s86, s71
	s_add_i32 s83, s84, 0x2000
	s_add_u32 s50, s56, 0x10080
	s_addc_u32 s51, s57, 0
	s_add_i32 s92, s85, s71
	s_add_i32 s91, s92, 0x2000
	v_lshl_add_u64 v[140:141], s[60:61], 0, v[128:129]
	ds_read_b128 v[186:189], v153
	ds_read_b128 v[190:193], v153 offset:1024
	ds_read_b128 v[194:197], v153 offset:2048
	ds_read_b128 v[198:201], v153 offset:3072
	ds_read_b128 v[202:205], v153 offset:4096
	ds_read_b128 v[206:209], v153 offset:5120
	ds_read_b128 v[214:217], v153 offset:6144
	ds_read_b128 v[218:221], v153 offset:7168
	global_load_lds_dwordx4 v[140:141], off
	v_lshl_add_u64 v[140:141], s[60:61], 0, v[132:133]
	s_mov_b32 m0, s93
	s_nop 0
	global_load_lds_dwordx4 v[140:141], off
	s_waitcnt vmcnt(8)
	s_waitcnt lgkmcnt(0)
	s_barrier
	s_setprio 1
	s_waitcnt lgkmcnt(0)
	v_mfma_f32_16x16x32_bf16 v[124:127], v[154:157], v[186:189], v[124:127]
	v_mfma_f32_16x16x32_bf16 v[120:123], v[162:165], v[186:189], v[120:123]
	v_mfma_f32_16x16x32_bf16 v[116:119], v[154:157], v[194:197], v[116:119]
	v_mfma_f32_16x16x32_bf16 v[108:111], v[162:165], v[194:197], v[108:111]
	v_mfma_f32_16x16x32_bf16 v[100:103], v[154:157], v[202:205], v[100:103]
	v_mfma_f32_16x16x32_bf16 v[92:95], v[162:165], v[202:205], v[92:95]
	v_mfma_f32_16x16x32_bf16 v[84:87], v[154:157], v[214:217], v[84:87]
	v_mfma_f32_16x16x32_bf16 v[76:79], v[162:165], v[214:217], v[76:79]
	v_mfma_f32_16x16x32_bf16 v[124:127], v[158:161], v[190:193], v[124:127]
	v_mfma_f32_16x16x32_bf16 v[120:123], v[166:169], v[190:193], v[120:123]
	v_mfma_f32_16x16x32_bf16 v[116:119], v[158:161], v[198:201], v[116:119]
	v_mfma_f32_16x16x32_bf16 v[108:111], v[166:169], v[198:201], v[108:111]
	v_mfma_f32_16x16x32_bf16 v[100:103], v[158:161], v[206:209], v[100:103]
	v_mfma_f32_16x16x32_bf16 v[92:95], v[166:169], v[206:209], v[92:95]
	v_mfma_f32_16x16x32_bf16 v[84:87], v[158:161], v[218:221], v[84:87]
	v_mfma_f32_16x16x32_bf16 v[76:79], v[166:169], v[218:221], v[76:79]
	v_mfma_f32_16x16x32_bf16 v[112:115], v[170:173], v[186:189], v[112:115]
	v_mfma_f32_16x16x32_bf16 v[104:107], v[178:181], v[186:189], v[104:107]
	v_mfma_f32_16x16x32_bf16 v[96:99], v[170:173], v[194:197], v[96:99]
	v_mfma_f32_16x16x32_bf16 v[88:91], v[178:181], v[194:197], v[88:91]
	v_mfma_f32_16x16x32_bf16 v[80:83], v[170:173], v[202:205], v[80:83]
	v_mfma_f32_16x16x32_bf16 v[72:75], v[178:181], v[202:205], v[72:75]
	v_mfma_f32_16x16x32_bf16 v[68:71], v[170:173], v[214:217], v[68:71]
	v_mfma_f32_16x16x32_bf16 v[64:67], v[178:181], v[214:217], v[64:67]
	v_mfma_f32_16x16x32_bf16 v[112:115], v[174:177], v[190:193], v[112:115]
	v_mfma_f32_16x16x32_bf16 v[104:107], v[182:185], v[190:193], v[104:107]
	v_mfma_f32_16x16x32_bf16 v[96:99], v[174:177], v[198:201], v[96:99]
	v_mfma_f32_16x16x32_bf16 v[88:91], v[182:185], v[198:201], v[88:91]
	v_mfma_f32_16x16x32_bf16 v[80:83], v[174:177], v[206:209], v[80:83]
	v_mfma_f32_16x16x32_bf16 v[72:75], v[182:185], v[206:209], v[72:75]
	v_mfma_f32_16x16x32_bf16 v[68:71], v[174:177], v[218:221], v[68:71]
	v_mfma_f32_16x16x32_bf16 v[64:67], v[182:185], v[218:221], v[64:67]
	s_setprio 0
	s_barrier
	s_mov_b32 m0, s90
	v_lshl_add_u64 v[140:141], s[56:57], 0, v[130:131]
	ds_read_b128 v[186:189], v153 offset:16384
	ds_read_b128 v[190:193], v153 offset:17408
	ds_read_b128 v[194:197], v153 offset:18432
	ds_read_b128 v[198:201], v153 offset:19456
	ds_read_b128 v[202:205], v153 offset:20480
	ds_read_b128 v[206:209], v153 offset:21504
	ds_read_b128 v[214:217], v153 offset:22528
	ds_read_b128 v[218:221], v153 offset:23552
	global_load_lds_dwordx4 v[140:141], off
	v_lshl_add_u64 v[210:211], s[56:57], 0, v[134:135]
	s_mov_b32 m0, s87
	v_lshl_add_u64 v[222:223], s[58:59], 0, v[130:131]
	global_load_lds_dwordx4 v[210:211], off
	s_mov_b32 m0, s89
	v_lshl_add_u64 v[224:225], s[54:55], 0, v[132:133]
	global_load_lds_dwordx4 v[222:223], off
	v_lshl_add_u64 v[222:223], s[58:59], 0, v[134:135]
	s_mov_b32 m0, s88
	s_nop 0
	global_load_lds_dwordx4 v[222:223], off
	v_lshl_add_u64 v[222:223], s[54:55], 0, v[128:129]
	s_mov_b32 m0, s72
	s_nop 0
	global_load_lds_dwordx4 v[222:223], off
	s_mov_b32 m0, s73
	s_nop 0
	global_load_lds_dwordx4 v[224:225], off
	s_waitcnt vmcnt(8)
	s_waitcnt lgkmcnt(0)
	s_barrier
	s_setprio 1
	s_waitcnt lgkmcnt(0)
	v_mfma_f32_16x16x32_bf16 v[60:63], v[154:157], v[186:189], v[60:63]
	v_mfma_f32_16x16x32_bf16 v[56:59], v[162:165], v[186:189], v[56:59]
	v_mfma_f32_16x16x32_bf16 v[52:55], v[154:157], v[194:197], v[52:55]
	v_mfma_f32_16x16x32_bf16 v[44:47], v[162:165], v[194:197], v[44:47]
	v_mfma_f32_16x16x32_bf16 v[36:39], v[154:157], v[202:205], v[36:39]
	v_mfma_f32_16x16x32_bf16 v[28:31], v[162:165], v[202:205], v[28:31]
	v_mfma_f32_16x16x32_bf16 v[20:23], v[154:157], v[214:217], v[20:23]
	v_mfma_f32_16x16x32_bf16 v[12:15], v[162:165], v[214:217], v[12:15]
	v_mfma_f32_16x16x32_bf16 v[60:63], v[158:161], v[190:193], v[60:63]
	v_mfma_f32_16x16x32_bf16 v[56:59], v[166:169], v[190:193], v[56:59]
	v_mfma_f32_16x16x32_bf16 v[52:55], v[158:161], v[198:201], v[52:55]
	v_mfma_f32_16x16x32_bf16 v[44:47], v[166:169], v[198:201], v[44:47]
	v_mfma_f32_16x16x32_bf16 v[36:39], v[158:161], v[206:209], v[36:39]
	v_mfma_f32_16x16x32_bf16 v[28:31], v[166:169], v[206:209], v[28:31]
	v_mfma_f32_16x16x32_bf16 v[20:23], v[158:161], v[218:221], v[20:23]
	v_mfma_f32_16x16x32_bf16 v[12:15], v[166:169], v[218:221], v[12:15]
	v_mfma_f32_16x16x32_bf16 v[48:51], v[170:173], v[186:189], v[48:51]
	v_mfma_f32_16x16x32_bf16 v[40:43], v[178:181], v[186:189], v[40:43]
	v_mfma_f32_16x16x32_bf16 v[32:35], v[170:173], v[194:197], v[32:35]
	v_mfma_f32_16x16x32_bf16 v[24:27], v[178:181], v[194:197], v[24:27]
	v_mfma_f32_16x16x32_bf16 v[16:19], v[170:173], v[202:205], v[16:19]
	v_mfma_f32_16x16x32_bf16 v[8:11], v[178:181], v[202:205], v[8:11]
	v_mfma_f32_16x16x32_bf16 v[4:7], v[170:173], v[214:217], v[4:7]
	v_mfma_f32_16x16x32_bf16 v[0:3], v[178:181], v[214:217], v[0:3]
	v_mfma_f32_16x16x32_bf16 v[48:51], v[174:177], v[190:193], v[48:51]
	v_mfma_f32_16x16x32_bf16 v[40:43], v[182:185], v[190:193], v[40:43]
	v_mfma_f32_16x16x32_bf16 v[32:35], v[174:177], v[198:201], v[32:35]
	v_mfma_f32_16x16x32_bf16 v[24:27], v[182:185], v[198:201], v[24:27]
	v_mfma_f32_16x16x32_bf16 v[16:19], v[174:177], v[206:209], v[16:19]
	v_mfma_f32_16x16x32_bf16 v[8:11], v[182:185], v[206:209], v[8:11]
	v_mfma_f32_16x16x32_bf16 v[4:7], v[174:177], v[218:221], v[4:7]
	v_mfma_f32_16x16x32_bf16 v[0:3], v[182:185], v[218:221], v[0:3]
	s_setprio 0
	s_barrier
	v_add_u32_e32 v166, s86, v151
	v_add_u32_e32 v182, s85, v151
	ds_read_b128 v[154:157], v166
	ds_read_b128 v[158:161], v166 offset:1024
	ds_read_b128 v[162:165], v166 offset:2048
	ds_read_b128 v[166:169], v166 offset:3072
	ds_read_b128 v[170:173], v182
	ds_read_b128 v[174:177], v182 offset:1024
	ds_read_b128 v[178:181], v182 offset:2048
	ds_read_b128 v[182:185], v182 offset:3072
	s_mov_b32 m0, s74
	v_lshl_add_u64 v[226:227], s[52:53], 0, v[128:129]
	ds_read_b128 v[186:189], v153 offset:32768
	ds_read_b128 v[190:193], v153 offset:33792
	ds_read_b128 v[194:197], v153 offset:34816
	ds_read_b128 v[198:201], v153 offset:35840
	ds_read_b128 v[202:205], v153 offset:36864
	ds_read_b128 v[206:209], v153 offset:37888
	ds_read_b128 v[214:217], v153 offset:38912
	ds_read_b128 v[218:221], v153 offset:39936
	global_load_lds_dwordx4 v[226:227], off
	v_lshl_add_u64 v[226:227], s[52:53], 0, v[132:133]
	s_mov_b32 m0, s75
	s_nop 0
	global_load_lds_dwordx4 v[226:227], off
	s_waitcnt vmcnt(8)
	s_waitcnt lgkmcnt(0)
	s_barrier
	s_setprio 1
	s_waitcnt lgkmcnt(0)
	v_mfma_f32_16x16x32_bf16 v[124:127], v[154:157], v[186:189], v[124:127]
	v_mfma_f32_16x16x32_bf16 v[120:123], v[162:165], v[186:189], v[120:123]
	v_mfma_f32_16x16x32_bf16 v[116:119], v[154:157], v[194:197], v[116:119]
	v_mfma_f32_16x16x32_bf16 v[108:111], v[162:165], v[194:197], v[108:111]
	v_mfma_f32_16x16x32_bf16 v[100:103], v[154:157], v[202:205], v[100:103]
	v_mfma_f32_16x16x32_bf16 v[92:95], v[162:165], v[202:205], v[92:95]
	v_mfma_f32_16x16x32_bf16 v[84:87], v[154:157], v[214:217], v[84:87]
	v_mfma_f32_16x16x32_bf16 v[76:79], v[162:165], v[214:217], v[76:79]
	v_mfma_f32_16x16x32_bf16 v[124:127], v[158:161], v[190:193], v[124:127]
	v_mfma_f32_16x16x32_bf16 v[120:123], v[166:169], v[190:193], v[120:123]
	v_mfma_f32_16x16x32_bf16 v[116:119], v[158:161], v[198:201], v[116:119]
	v_mfma_f32_16x16x32_bf16 v[108:111], v[166:169], v[198:201], v[108:111]
	v_mfma_f32_16x16x32_bf16 v[100:103], v[158:161], v[206:209], v[100:103]
	v_mfma_f32_16x16x32_bf16 v[92:95], v[166:169], v[206:209], v[92:95]
	v_mfma_f32_16x16x32_bf16 v[84:87], v[158:161], v[218:221], v[84:87]
	v_mfma_f32_16x16x32_bf16 v[76:79], v[166:169], v[218:221], v[76:79]
	v_mfma_f32_16x16x32_bf16 v[112:115], v[170:173], v[186:189], v[112:115]
	v_mfma_f32_16x16x32_bf16 v[104:107], v[178:181], v[186:189], v[104:107]
	v_mfma_f32_16x16x32_bf16 v[96:99], v[170:173], v[194:197], v[96:99]
	v_mfma_f32_16x16x32_bf16 v[88:91], v[178:181], v[194:197], v[88:91]
	v_mfma_f32_16x16x32_bf16 v[80:83], v[170:173], v[202:205], v[80:83]
	v_mfma_f32_16x16x32_bf16 v[72:75], v[178:181], v[202:205], v[72:75]
	v_mfma_f32_16x16x32_bf16 v[68:71], v[170:173], v[214:217], v[68:71]
	v_mfma_f32_16x16x32_bf16 v[64:67], v[178:181], v[214:217], v[64:67]
	v_mfma_f32_16x16x32_bf16 v[112:115], v[174:177], v[190:193], v[112:115]
	v_mfma_f32_16x16x32_bf16 v[104:107], v[182:185], v[190:193], v[104:107]
	v_mfma_f32_16x16x32_bf16 v[96:99], v[174:177], v[198:201], v[96:99]
	v_mfma_f32_16x16x32_bf16 v[88:91], v[182:185], v[198:201], v[88:91]
	v_mfma_f32_16x16x32_bf16 v[80:83], v[174:177], v[206:209], v[80:83]
	v_mfma_f32_16x16x32_bf16 v[72:75], v[182:185], v[206:209], v[72:75]
	v_mfma_f32_16x16x32_bf16 v[68:71], v[174:177], v[218:221], v[68:71]
	v_mfma_f32_16x16x32_bf16 v[64:67], v[182:185], v[218:221], v[64:67]
	s_setprio 0
	s_barrier
	s_mov_b32 m0, s84
	v_lshl_add_u64 v[140:141], v[140:141], 0, s[16:17]
	ds_read_b128 v[186:189], v153 offset:49152
	ds_read_b128 v[190:193], v153 offset:50176
	ds_read_b128 v[194:197], v153 offset:51200
	ds_read_b128 v[198:201], v153 offset:52224
	ds_read_b128 v[202:205], v153 offset:53248
	ds_read_b128 v[206:209], v153 offset:54272
	ds_read_b128 v[214:217], v153 offset:55296
	ds_read_b128 v[218:221], v153 offset:56320
	global_load_lds_dwordx4 v[140:141], off
	v_lshl_add_u64 v[140:141], v[210:211], 0, s[16:17]
	s_mov_b32 m0, s83
	s_nop 0
	global_load_lds_dwordx4 v[140:141], off
	v_lshl_add_u64 v[140:141], s[50:51], 0, v[130:131]
	s_mov_b32 m0, s92
	s_nop 0
	global_load_lds_dwordx4 v[140:141], off
	v_lshl_add_u64 v[140:141], s[50:51], 0, v[134:135]
	s_mov_b32 m0, s91
	s_nop 0
	global_load_lds_dwordx4 v[140:141], off
	v_lshl_add_u64 v[140:141], v[222:223], 0, s[16:17]
	s_mov_b32 m0, s77
	s_nop 0
	global_load_lds_dwordx4 v[140:141], off
	v_lshl_add_u64 v[140:141], v[224:225], 0, s[16:17]
	s_mov_b32 m0, s78
	s_nop 0
	global_load_lds_dwordx4 v[140:141], off
	s_waitcnt vmcnt(8)
	s_waitcnt lgkmcnt(0)
	s_barrier
	s_setprio 1
	s_waitcnt lgkmcnt(0)
	v_mfma_f32_16x16x32_bf16 v[60:63], v[154:157], v[186:189], v[60:63]
	v_mfma_f32_16x16x32_bf16 v[56:59], v[162:165], v[186:189], v[56:59]
	v_mfma_f32_16x16x32_bf16 v[52:55], v[154:157], v[194:197], v[52:55]
	v_mfma_f32_16x16x32_bf16 v[44:47], v[162:165], v[194:197], v[44:47]
	v_mfma_f32_16x16x32_bf16 v[36:39], v[154:157], v[202:205], v[36:39]
	v_mfma_f32_16x16x32_bf16 v[28:31], v[162:165], v[202:205], v[28:31]
	v_mfma_f32_16x16x32_bf16 v[20:23], v[154:157], v[214:217], v[20:23]
	v_mfma_f32_16x16x32_bf16 v[12:15], v[162:165], v[214:217], v[12:15]
	v_mfma_f32_16x16x32_bf16 v[60:63], v[158:161], v[190:193], v[60:63]
	v_mfma_f32_16x16x32_bf16 v[56:59], v[166:169], v[190:193], v[56:59]
	v_mfma_f32_16x16x32_bf16 v[52:55], v[158:161], v[198:201], v[52:55]
	v_mfma_f32_16x16x32_bf16 v[44:47], v[166:169], v[198:201], v[44:47]
	v_mfma_f32_16x16x32_bf16 v[36:39], v[158:161], v[206:209], v[36:39]
	v_mfma_f32_16x16x32_bf16 v[28:31], v[166:169], v[206:209], v[28:31]
	v_mfma_f32_16x16x32_bf16 v[20:23], v[158:161], v[218:221], v[20:23]
	v_mfma_f32_16x16x32_bf16 v[12:15], v[166:169], v[218:221], v[12:15]
	v_mfma_f32_16x16x32_bf16 v[48:51], v[170:173], v[186:189], v[48:51]
	v_mfma_f32_16x16x32_bf16 v[40:43], v[178:181], v[186:189], v[40:43]
	v_mfma_f32_16x16x32_bf16 v[32:35], v[170:173], v[194:197], v[32:35]
	v_mfma_f32_16x16x32_bf16 v[24:27], v[178:181], v[194:197], v[24:27]
	v_mfma_f32_16x16x32_bf16 v[16:19], v[170:173], v[202:205], v[16:19]
	v_mfma_f32_16x16x32_bf16 v[8:11], v[178:181], v[202:205], v[8:11]
	v_mfma_f32_16x16x32_bf16 v[4:7], v[170:173], v[214:217], v[4:7]
	v_mfma_f32_16x16x32_bf16 v[0:3], v[178:181], v[214:217], v[0:3]
	v_mfma_f32_16x16x32_bf16 v[48:51], v[174:177], v[190:193], v[48:51]
	v_mfma_f32_16x16x32_bf16 v[40:43], v[182:185], v[190:193], v[40:43]
	v_mfma_f32_16x16x32_bf16 v[32:35], v[174:177], v[198:201], v[32:35]
	v_mfma_f32_16x16x32_bf16 v[24:27], v[182:185], v[198:201], v[24:27]
	v_mfma_f32_16x16x32_bf16 v[16:19], v[174:177], v[206:209], v[16:19]
	v_mfma_f32_16x16x32_bf16 v[8:11], v[182:185], v[206:209], v[8:11]
	v_mfma_f32_16x16x32_bf16 v[4:7], v[174:177], v[218:221], v[4:7]
	v_mfma_f32_16x16x32_bf16 v[0:3], v[182:185], v[218:221], v[0:3]
	s_setprio 0
	s_barrier
	s_movk_i32 s52, 0x100
	s_andn2_b64 vcc, exec, s[48:49]
	s_mov_b64 s[50:51], -1
	s_mov_b64 s[48:49], 0
	s_cbranch_vccz .LBB0_144
	s_and_b64 vcc, exec, s[30:31]
	s_cbranch_vccnz .LBB0_148
	s_cmp_gt_i32 s76, 7
	s_cbranch_scc0 .LBB0_149

.LBB0_226:
	ds_read_b128 v[144:147], v153
	ds_read_b128 v[156:159], v153 offset:1024
	ds_read_b128 v[160:163], v153 offset:2048
	ds_read_b128 v[164:167], v153 offset:3072
	ds_read_b128 v[168:171], v154
	ds_read_b128 v[172:175], v154 offset:1024
	ds_read_b128 v[176:179], v154 offset:2048
	ds_read_b128 v[180:183], v154 offset:3072
	s_add_u32 s36, s30, 0x100
	s_addc_u32 s37, s31, 0
	s_cmpk_eq_i32 s60, 0x54
	s_cselect_b32 s41, s5, s37
	s_cselect_b32 s40, s4, s36
	s_cselect_b32 s39, s29, s59
	s_cselect_b32 s38, s28, s58
	v_lshl_add_u64 v[148:149], s[30:31], 0, v[136:137]
	s_add_i32 m0, s45, 0xc000
	ds_read_b128 v[184:187], v155
	ds_read_b128 v[188:191], v155 offset:1024
	ds_read_b128 v[192:195], v155 offset:2048
	ds_read_b128 v[196:199], v155 offset:3072
	ds_read_b128 v[200:203], v155 offset:4096
	ds_read_b128 v[204:207], v155 offset:5120
	ds_read_b128 v[208:211], v155 offset:6144
	ds_read_b128 v[214:217], v155 offset:7168
	global_load_lds_dwordx4 v[148:149], off
	v_lshl_add_u64 v[148:149], s[30:31], 0, v[138:139]
	s_add_i32 m0, s45, 0xe000
	s_nop 0
	global_load_lds_dwordx4 v[148:149], off
	s_waitcnt vmcnt(8)
	s_waitcnt lgkmcnt(0)
	s_barrier
	s_setprio 1
	s_waitcnt lgkmcnt(0)
	v_mfma_f32_16x16x32_bf16 v[124:127], v[144:147], v[184:187], v[124:127]
	v_mfma_f32_16x16x32_bf16 v[120:123], v[160:163], v[184:187], v[120:123]
	v_mfma_f32_16x16x32_bf16 v[108:111], v[144:147], v[192:195], v[108:111]
	v_mfma_f32_16x16x32_bf16 v[104:107], v[160:163], v[192:195], v[104:107]
	v_mfma_f32_16x16x32_bf16 v[92:95], v[144:147], v[200:203], v[92:95]
	v_mfma_f32_16x16x32_bf16 v[88:91], v[160:163], v[200:203], v[88:91]
	v_mfma_f32_16x16x32_bf16 v[76:79], v[144:147], v[208:211], v[76:79]
	v_mfma_f32_16x16x32_bf16 v[72:75], v[160:163], v[208:211], v[72:75]
	v_mfma_f32_16x16x32_bf16 v[124:127], v[156:159], v[188:191], v[124:127]
	v_mfma_f32_16x16x32_bf16 v[120:123], v[164:167], v[188:191], v[120:123]
	v_mfma_f32_16x16x32_bf16 v[108:111], v[156:159], v[196:199], v[108:111]
	v_mfma_f32_16x16x32_bf16 v[104:107], v[164:167], v[196:199], v[104:107]
	v_mfma_f32_16x16x32_bf16 v[92:95], v[156:159], v[204:207], v[92:95]
	v_mfma_f32_16x16x32_bf16 v[88:91], v[164:167], v[204:207], v[88:91]
	v_mfma_f32_16x16x32_bf16 v[76:79], v[156:159], v[214:217], v[76:79]
	v_mfma_f32_16x16x32_bf16 v[72:75], v[164:167], v[214:217], v[72:75]
	v_mfma_f32_16x16x32_bf16 v[116:119], v[168:171], v[184:187], v[116:119]
	v_mfma_f32_16x16x32_bf16 v[112:115], v[176:179], v[184:187], v[112:115]
	v_mfma_f32_16x16x32_bf16 v[100:103], v[168:171], v[192:195], v[100:103]
	v_mfma_f32_16x16x32_bf16 v[96:99], v[176:179], v[192:195], v[96:99]
	v_mfma_f32_16x16x32_bf16 v[84:87], v[168:171], v[200:203], v[84:87]
	v_mfma_f32_16x16x32_bf16 v[80:83], v[176:179], v[200:203], v[80:83]
	v_mfma_f32_16x16x32_bf16 v[68:71], v[168:171], v[208:211], v[68:71]
	v_mfma_f32_16x16x32_bf16 v[64:67], v[176:179], v[208:211], v[64:67]
	v_mfma_f32_16x16x32_bf16 v[116:119], v[172:175], v[188:191], v[116:119]
	v_mfma_f32_16x16x32_bf16 v[112:115], v[180:183], v[188:191], v[112:115]
	v_mfma_f32_16x16x32_bf16 v[100:103], v[172:175], v[196:199], v[100:103]
	v_mfma_f32_16x16x32_bf16 v[96:99], v[180:183], v[196:199], v[96:99]
	v_mfma_f32_16x16x32_bf16 v[84:87], v[172:175], v[204:207], v[84:87]
	v_mfma_f32_16x16x32_bf16 v[80:83], v[180:183], v[204:207], v[80:83]
	v_mfma_f32_16x16x32_bf16 v[68:71], v[172:175], v[214:217], v[68:71]
	v_mfma_f32_16x16x32_bf16 v[64:67], v[180:183], v[214:217], v[64:67]
	s_setprio 0
	s_barrier
	s_add_i32 s30, s53, s43
	v_lshl_add_u64 v[148:149], s[38:39], 0, v[132:133]
	s_mov_b32 m0, s30
	ds_read_b128 v[184:187], v155 offset:16384
	ds_read_b128 v[188:191], v155 offset:17408
	ds_read_b128 v[192:195], v155 offset:18432
	ds_read_b128 v[196:199], v155 offset:19456
	ds_read_b128 v[200:203], v155 offset:20480
	ds_read_b128 v[204:207], v155 offset:21504
	ds_read_b128 v[208:211], v155 offset:22528
	ds_read_b128 v[214:217], v155 offset:23552
	global_load_lds_dwordx4 v[148:149], off
	s_add_i32 m0, s30, 0x2000
	s_add_u32 s30, s38, 0x160000
	v_lshl_add_u64 v[218:219], s[38:39], 0, v[128:129]
	s_addc_u32 s31, s39, 0
	s_add_i32 s61, s54, s43
	global_load_lds_dwordx4 v[218:219], off
	v_lshl_add_u64 v[220:221], s[30:31], 0, v[132:133]
	s_mov_b32 m0, s61
	v_lshl_add_u64 v[222:223], s[40:41], 0, v[130:131]
	global_load_lds_dwordx4 v[220:221], off
	v_lshl_add_u64 v[220:221], s[30:31], 0, v[128:129]
	s_add_i32 m0, s61, 0x2000
	s_nop 0
	global_load_lds_dwordx4 v[220:221], off
	v_lshl_add_u64 v[220:221], s[40:41], 0, v[134:135]
	s_mov_b32 m0, s45
	s_nop 0
	global_load_lds_dwordx4 v[220:221], off
	s_mov_b32 m0, s46
	s_nop 0
	global_load_lds_dwordx4 v[222:223], off
	s_waitcnt vmcnt(8)
	s_waitcnt lgkmcnt(0)
	s_barrier
	s_setprio 1
	s_waitcnt lgkmcnt(0)
	v_mfma_f32_16x16x32_bf16 v[60:63], v[144:147], v[184:187], v[60:63]
	v_mfma_f32_16x16x32_bf16 v[56:59], v[160:163], v[184:187], v[56:59]
	v_mfma_f32_16x16x32_bf16 v[44:47], v[144:147], v[192:195], v[44:47]
	v_mfma_f32_16x16x32_bf16 v[40:43], v[160:163], v[192:195], v[40:43]
	v_mfma_f32_16x16x32_bf16 v[28:31], v[144:147], v[200:203], v[28:31]
	v_mfma_f32_16x16x32_bf16 v[24:27], v[160:163], v[200:203], v[24:27]
	v_mfma_f32_16x16x32_bf16 v[12:15], v[144:147], v[208:211], v[12:15]
	v_mfma_f32_16x16x32_bf16 v[8:11], v[160:163], v[208:211], v[8:11]
	v_mfma_f32_16x16x32_bf16 v[60:63], v[156:159], v[188:191], v[60:63]
	v_mfma_f32_16x16x32_bf16 v[56:59], v[164:167], v[188:191], v[56:59]
	v_mfma_f32_16x16x32_bf16 v[44:47], v[156:159], v[196:199], v[44:47]
	v_mfma_f32_16x16x32_bf16 v[40:43], v[164:167], v[196:199], v[40:43]
	v_mfma_f32_16x16x32_bf16 v[28:31], v[156:159], v[204:207], v[28:31]
	v_mfma_f32_16x16x32_bf16 v[24:27], v[164:167], v[204:207], v[24:27]
	v_mfma_f32_16x16x32_bf16 v[12:15], v[156:159], v[214:217], v[12:15]
	v_mfma_f32_16x16x32_bf16 v[8:11], v[164:167], v[214:217], v[8:11]
	v_mfma_f32_16x16x32_bf16 v[52:55], v[168:171], v[184:187], v[52:55]
	v_mfma_f32_16x16x32_bf16 v[48:51], v[176:179], v[184:187], v[48:51]
	v_mfma_f32_16x16x32_bf16 v[36:39], v[168:171], v[192:195], v[36:39]
	v_mfma_f32_16x16x32_bf16 v[32:35], v[176:179], v[192:195], v[32:35]
	v_mfma_f32_16x16x32_bf16 v[20:23], v[168:171], v[200:203], v[20:23]
	v_mfma_f32_16x16x32_bf16 v[16:19], v[176:179], v[200:203], v[16:19]
	v_mfma_f32_16x16x32_bf16 v[4:7], v[168:171], v[208:211], v[4:7]
	v_mfma_f32_16x16x32_bf16 v[0:3], v[176:179], v[208:211], v[0:3]
	v_mfma_f32_16x16x32_bf16 v[52:55], v[172:175], v[188:191], v[52:55]
	v_mfma_f32_16x16x32_bf16 v[48:51], v[180:183], v[188:191], v[48:51]
	v_mfma_f32_16x16x32_bf16 v[36:39], v[172:175], v[196:199], v[36:39]
	v_mfma_f32_16x16x32_bf16 v[32:35], v[180:183], v[196:199], v[32:35]
	v_mfma_f32_16x16x32_bf16 v[20:23], v[172:175], v[204:207], v[20:23]
	v_mfma_f32_16x16x32_bf16 v[16:19], v[180:183], v[204:207], v[16:19]
	v_mfma_f32_16x16x32_bf16 v[4:7], v[172:175], v[214:217], v[4:7]
	v_mfma_f32_16x16x32_bf16 v[0:3], v[180:183], v[214:217], v[0:3]
	s_setprio 0
	s_barrier
	s_add_i32 s61, 0, 0x18000
	s_add_i32 s62, 0, 0x1c000
	v_add_u32_e32 v164, s61, v151
	v_add_u32_e32 v180, s62, v151
	ds_read_b128 v[144:147], v164
	ds_read_b128 v[156:159], v164 offset:1024
	ds_read_b128 v[160:163], v164 offset:2048
	ds_read_b128 v[164:167], v164 offset:3072
	ds_read_b128 v[168:171], v180
	ds_read_b128 v[172:175], v180 offset:1024
	ds_read_b128 v[176:179], v180 offset:2048
	ds_read_b128 v[180:183], v180 offset:3072
	s_add_u32 s30, s40, 0x160000
	s_addc_u32 s31, s41, 0
	s_mov_b32 m0, s47
	v_lshl_add_u64 v[224:225], s[30:31], 0, v[134:135]
	ds_read_b128 v[184:187], v155 offset:32768
	ds_read_b128 v[188:191], v155 offset:33792
	ds_read_b128 v[192:195], v155 offset:34816
	ds_read_b128 v[196:199], v155 offset:35840
	ds_read_b128 v[200:203], v155 offset:36864
	ds_read_b128 v[204:207], v155 offset:37888
	ds_read_b128 v[208:211], v155 offset:38912
	ds_read_b128 v[214:217], v155 offset:39936
	global_load_lds_dwordx4 v[224:225], off
	v_lshl_add_u64 v[224:225], s[30:31], 0, v[130:131]
	s_mov_b32 m0, s48
	s_nop 0
	global_load_lds_dwordx4 v[224:225], off
	s_waitcnt vmcnt(8)
	s_waitcnt lgkmcnt(0)
	s_barrier
	s_setprio 1
	s_waitcnt lgkmcnt(0)
	v_mfma_f32_16x16x32_bf16 v[124:127], v[144:147], v[184:187], v[124:127]
	v_mfma_f32_16x16x32_bf16 v[120:123], v[160:163], v[184:187], v[120:123]
	v_mfma_f32_16x16x32_bf16 v[108:111], v[144:147], v[192:195], v[108:111]
	v_mfma_f32_16x16x32_bf16 v[104:107], v[160:163], v[192:195], v[104:107]
	v_mfma_f32_16x16x32_bf16 v[92:95], v[144:147], v[200:203], v[92:95]
	v_mfma_f32_16x16x32_bf16 v[88:91], v[160:163], v[200:203], v[88:91]
	v_mfma_f32_16x16x32_bf16 v[76:79], v[144:147], v[208:211], v[76:79]
	v_mfma_f32_16x16x32_bf16 v[72:75], v[160:163], v[208:211], v[72:75]
	v_mfma_f32_16x16x32_bf16 v[124:127], v[156:159], v[188:191], v[124:127]
	v_mfma_f32_16x16x32_bf16 v[120:123], v[164:167], v[188:191], v[120:123]
	v_mfma_f32_16x16x32_bf16 v[108:111], v[156:159], v[196:199], v[108:111]
	v_mfma_f32_16x16x32_bf16 v[104:107], v[164:167], v[196:199], v[104:107]
	v_mfma_f32_16x16x32_bf16 v[92:95], v[156:159], v[204:207], v[92:95]
	v_mfma_f32_16x16x32_bf16 v[88:91], v[164:167], v[204:207], v[88:91]
	v_mfma_f32_16x16x32_bf16 v[76:79], v[156:159], v[214:217], v[76:79]
	v_mfma_f32_16x16x32_bf16 v[72:75], v[164:167], v[214:217], v[72:75]
	v_mfma_f32_16x16x32_bf16 v[116:119], v[168:171], v[184:187], v[116:119]
	v_mfma_f32_16x16x32_bf16 v[112:115], v[176:179], v[184:187], v[112:115]
	v_mfma_f32_16x16x32_bf16 v[100:103], v[168:171], v[192:195], v[100:103]
	v_mfma_f32_16x16x32_bf16 v[96:99], v[176:179], v[192:195], v[96:99]
	v_mfma_f32_16x16x32_bf16 v[84:87], v[168:171], v[200:203], v[84:87]
	v_mfma_f32_16x16x32_bf16 v[80:83], v[176:179], v[200:203], v[80:83]
	v_mfma_f32_16x16x32_bf16 v[68:71], v[168:171], v[208:211], v[68:71]
	v_mfma_f32_16x16x32_bf16 v[64:67], v[176:179], v[208:211], v[64:67]
	v_mfma_f32_16x16x32_bf16 v[116:119], v[172:175], v[188:191], v[116:119]
	v_mfma_f32_16x16x32_bf16 v[112:115], v[180:183], v[188:191], v[112:115]
	v_mfma_f32_16x16x32_bf16 v[100:103], v[172:175], v[196:199], v[100:103]
	v_mfma_f32_16x16x32_bf16 v[96:99], v[180:183], v[196:199], v[96:99]
	v_mfma_f32_16x16x32_bf16 v[84:87], v[172:175], v[204:207], v[84:87]
	v_mfma_f32_16x16x32_bf16 v[80:83], v[180:183], v[204:207], v[80:83]
	v_mfma_f32_16x16x32_bf16 v[68:71], v[172:175], v[214:217], v[68:71]
	v_mfma_f32_16x16x32_bf16 v[64:67], v[180:183], v[214:217], v[64:67]
	s_setprio 0
	s_barrier
	s_add_i32 s30, s61, s43
	v_lshl_add_u64 v[148:149], v[148:149], 0, s[14:15]
	s_mov_b32 m0, s30
	ds_read_b128 v[184:187], v155 offset:49152
	ds_read_b128 v[188:191], v155 offset:50176
	ds_read_b128 v[192:195], v155 offset:51200
	ds_read_b128 v[196:199], v155 offset:52224
	ds_read_b128 v[200:203], v155 offset:53248
	ds_read_b128 v[204:207], v155 offset:54272
	ds_read_b128 v[208:211], v155 offset:55296
	ds_read_b128 v[214:217], v155 offset:56320
	global_load_lds_dwordx4 v[148:149], off
	s_add_i32 m0, s30, 0x2000
	s_add_u32 s30, s38, 0x160080
	v_lshl_add_u64 v[148:149], v[218:219], 0, s[14:15]
	s_addc_u32 s31, s39, 0
	s_add_i32 s38, s62, s43
	global_load_lds_dwordx4 v[148:149], off
	v_lshl_add_u64 v[148:149], s[30:31], 0, v[132:133]
	s_mov_b32 m0, s38
	s_nop 0
	global_load_lds_dwordx4 v[148:149], off
	v_lshl_add_u64 v[148:149], s[30:31], 0, v[128:129]
	s_add_i32 m0, s38, 0x2000
	s_nop 0
	global_load_lds_dwordx4 v[148:149], off
	v_lshl_add_u64 v[148:149], v[220:221], 0, s[14:15]
	s_mov_b32 m0, s50
	s_nop 0
	global_load_lds_dwordx4 v[148:149], off
	v_lshl_add_u64 v[148:149], v[222:223], 0, s[14:15]
	s_mov_b32 m0, s51
	s_nop 0
	global_load_lds_dwordx4 v[148:149], off
	s_waitcnt vmcnt(8)
	s_waitcnt lgkmcnt(0)
	s_barrier
	s_setprio 1
	s_waitcnt lgkmcnt(0)
	v_mfma_f32_16x16x32_bf16 v[60:63], v[144:147], v[184:187], v[60:63]
	v_mfma_f32_16x16x32_bf16 v[56:59], v[160:163], v[184:187], v[56:59]
	v_mfma_f32_16x16x32_bf16 v[44:47], v[144:147], v[192:195], v[44:47]
	v_mfma_f32_16x16x32_bf16 v[40:43], v[160:163], v[192:195], v[40:43]
	v_mfma_f32_16x16x32_bf16 v[28:31], v[144:147], v[200:203], v[28:31]
	v_mfma_f32_16x16x32_bf16 v[24:27], v[160:163], v[200:203], v[24:27]
	v_mfma_f32_16x16x32_bf16 v[12:15], v[144:147], v[208:211], v[12:15]
	v_mfma_f32_16x16x32_bf16 v[8:11], v[160:163], v[208:211], v[8:11]
	v_mfma_f32_16x16x32_bf16 v[60:63], v[156:159], v[188:191], v[60:63]
	v_mfma_f32_16x16x32_bf16 v[56:59], v[164:167], v[188:191], v[56:59]
	v_mfma_f32_16x16x32_bf16 v[44:47], v[156:159], v[196:199], v[44:47]
	v_mfma_f32_16x16x32_bf16 v[40:43], v[164:167], v[196:199], v[40:43]
	v_mfma_f32_16x16x32_bf16 v[28:31], v[156:159], v[204:207], v[28:31]
	v_mfma_f32_16x16x32_bf16 v[24:27], v[164:167], v[204:207], v[24:27]
	v_mfma_f32_16x16x32_bf16 v[12:15], v[156:159], v[214:217], v[12:15]
	v_mfma_f32_16x16x32_bf16 v[8:11], v[164:167], v[214:217], v[8:11]
	v_mfma_f32_16x16x32_bf16 v[52:55], v[168:171], v[184:187], v[52:55]
	v_mfma_f32_16x16x32_bf16 v[48:51], v[176:179], v[184:187], v[48:51]
	v_mfma_f32_16x16x32_bf16 v[36:39], v[168:171], v[192:195], v[36:39]
	v_mfma_f32_16x16x32_bf16 v[32:35], v[176:179], v[192:195], v[32:35]
	v_mfma_f32_16x16x32_bf16 v[20:23], v[168:171], v[200:203], v[20:23]
	v_mfma_f32_16x16x32_bf16 v[16:19], v[176:179], v[200:203], v[16:19]
	v_mfma_f32_16x16x32_bf16 v[4:7], v[168:171], v[208:211], v[4:7]
	v_mfma_f32_16x16x32_bf16 v[0:3], v[176:179], v[208:211], v[0:3]
	v_mfma_f32_16x16x32_bf16 v[52:55], v[172:175], v[188:191], v[52:55]
	v_mfma_f32_16x16x32_bf16 v[48:51], v[180:183], v[188:191], v[48:51]
	v_mfma_f32_16x16x32_bf16 v[36:39], v[172:175], v[196:199], v[36:39]
	v_mfma_f32_16x16x32_bf16 v[32:35], v[180:183], v[196:199], v[32:35]
	v_mfma_f32_16x16x32_bf16 v[20:23], v[172:175], v[204:207], v[20:23]
	v_mfma_f32_16x16x32_bf16 v[16:19], v[180:183], v[204:207], v[16:19]
	v_mfma_f32_16x16x32_bf16 v[4:7], v[172:175], v[214:217], v[4:7]
	v_mfma_f32_16x16x32_bf16 v[0:3], v[180:183], v[214:217], v[0:3]
	s_setprio 0
	s_barrier
	s_add_i32 s60, s60, 2
	s_add_u32 s58, s58, 0x100
	s_addc_u32 s59, s59, 0
	s_cmpk_gt_u32 s60, 0x55
	s_mov_b64 s[30:31], s[36:37]
	s_cbranch_scc0 .LBB0_226
	s_and_b64 vcc, exec, s[16:17]
	s_cbranch_vccz .LBB0_229
	s_barrier

.LBB0_374:
	ds_read_b128 v[144:147], v151
	ds_read_b128 v[154:157], v151 offset:1024
	ds_read_b128 v[158:161], v151 offset:2048
	ds_read_b128 v[162:165], v151 offset:3072
	ds_read_b128 v[166:169], v152
	ds_read_b128 v[170:173], v152 offset:1024
	ds_read_b128 v[174:177], v152 offset:2048
	ds_read_b128 v[178:181], v152 offset:3072
	s_add_u32 s26, s24, 0xfff80080
	s_addc_u32 s27, s25, -1
	s_cmp_eq_u32 s53, 28
	s_cselect_b32 s29, s17, s27
	s_cselect_b32 s28, s49, s26
	s_cselect_b32 s27, s15, s52
	s_cselect_b32 s26, s50, s51
	v_lshl_add_u64 v[210:211], s[24:25], 0, v[136:137]
	s_add_i32 m0, s23, 0xc000
	ds_read_b128 v[182:185], v153
	ds_read_b128 v[186:189], v153 offset:1024
	ds_read_b128 v[190:193], v153 offset:2048
	ds_read_b128 v[194:197], v153 offset:3072
	ds_read_b128 v[198:201], v153 offset:4096
	ds_read_b128 v[202:205], v153 offset:5120
	ds_read_b128 v[206:209], v153 offset:6144
	ds_read_b128 v[214:217], v153 offset:7168
	global_load_lds_dwordx4 v[210:211], off
	v_lshl_add_u64 v[210:211], s[24:25], 0, v[138:139]
	s_add_i32 m0, s23, 0xe000
	s_nop 0
	global_load_lds_dwordx4 v[210:211], off
	s_waitcnt vmcnt(8)
	s_waitcnt lgkmcnt(0)
	s_barrier
	s_setprio 1
	s_waitcnt lgkmcnt(0)
	v_mfma_f32_16x16x32_bf16 v[124:127], v[144:147], v[182:185], v[124:127]
	v_mfma_f32_16x16x32_bf16 v[120:123], v[158:161], v[182:185], v[120:123]
	v_mfma_f32_16x16x32_bf16 v[116:119], v[144:147], v[190:193], v[116:119]
	v_mfma_f32_16x16x32_bf16 v[108:111], v[158:161], v[190:193], v[108:111]
	v_mfma_f32_16x16x32_bf16 v[100:103], v[144:147], v[198:201], v[100:103]
	v_mfma_f32_16x16x32_bf16 v[92:95], v[158:161], v[198:201], v[92:95]
	v_mfma_f32_16x16x32_bf16 v[84:87], v[144:147], v[206:209], v[84:87]
	v_mfma_f32_16x16x32_bf16 v[76:79], v[158:161], v[206:209], v[76:79]
	v_mfma_f32_16x16x32_bf16 v[124:127], v[154:157], v[186:189], v[124:127]
	v_mfma_f32_16x16x32_bf16 v[120:123], v[162:165], v[186:189], v[120:123]
	v_mfma_f32_16x16x32_bf16 v[116:119], v[154:157], v[194:197], v[116:119]
	v_mfma_f32_16x16x32_bf16 v[108:111], v[162:165], v[194:197], v[108:111]
	v_mfma_f32_16x16x32_bf16 v[100:103], v[154:157], v[202:205], v[100:103]
	v_mfma_f32_16x16x32_bf16 v[92:95], v[162:165], v[202:205], v[92:95]
	v_mfma_f32_16x16x32_bf16 v[84:87], v[154:157], v[214:217], v[84:87]
	v_mfma_f32_16x16x32_bf16 v[76:79], v[162:165], v[214:217], v[76:79]
	v_mfma_f32_16x16x32_bf16 v[112:115], v[166:169], v[182:185], v[112:115]
	v_mfma_f32_16x16x32_bf16 v[104:107], v[174:177], v[182:185], v[104:107]
	v_mfma_f32_16x16x32_bf16 v[96:99], v[166:169], v[190:193], v[96:99]
	v_mfma_f32_16x16x32_bf16 v[88:91], v[174:177], v[190:193], v[88:91]
	v_mfma_f32_16x16x32_bf16 v[80:83], v[166:169], v[198:201], v[80:83]
	v_mfma_f32_16x16x32_bf16 v[72:75], v[174:177], v[198:201], v[72:75]
	v_mfma_f32_16x16x32_bf16 v[68:71], v[166:169], v[206:209], v[68:71]
	v_mfma_f32_16x16x32_bf16 v[64:67], v[174:177], v[206:209], v[64:67]
	v_mfma_f32_16x16x32_bf16 v[112:115], v[170:173], v[186:189], v[112:115]
	v_mfma_f32_16x16x32_bf16 v[104:107], v[178:181], v[186:189], v[104:107]
	v_mfma_f32_16x16x32_bf16 v[96:99], v[170:173], v[194:197], v[96:99]
	v_mfma_f32_16x16x32_bf16 v[88:91], v[178:181], v[194:197], v[88:91]
	v_mfma_f32_16x16x32_bf16 v[80:83], v[170:173], v[202:205], v[80:83]
	v_mfma_f32_16x16x32_bf16 v[72:75], v[178:181], v[202:205], v[72:75]
	v_mfma_f32_16x16x32_bf16 v[68:71], v[170:173], v[214:217], v[68:71]
	v_mfma_f32_16x16x32_bf16 v[64:67], v[178:181], v[214:217], v[64:67]
	s_setprio 0
	s_barrier
	s_add_i32 s54, s45, s35
	v_lshl_add_u64 v[210:211], s[26:27], 0, v[132:133]
	s_mov_b32 m0, s54
	ds_read_b128 v[182:185], v153 offset:16384
	ds_read_b128 v[186:189], v153 offset:17408
	ds_read_b128 v[190:193], v153 offset:18432
	ds_read_b128 v[194:197], v153 offset:19456
	ds_read_b128 v[198:201], v153 offset:20480
	ds_read_b128 v[202:205], v153 offset:21504
	ds_read_b128 v[206:209], v153 offset:22528
	ds_read_b128 v[214:217], v153 offset:23552
	global_load_lds_dwordx4 v[210:211], off
	s_add_i32 m0, s54, 0x2000
	s_add_u32 s54, s26, 0x80000
	v_lshl_add_u64 v[218:219], s[26:27], 0, v[128:129]
	s_addc_u32 s55, s27, 0
	s_add_i32 s56, s46, s35
	global_load_lds_dwordx4 v[218:219], off
	v_lshl_add_u64 v[220:221], s[54:55], 0, v[132:133]
	s_mov_b32 m0, s56
	v_lshl_add_u64 v[222:223], s[28:29], 0, v[130:131]
	global_load_lds_dwordx4 v[220:221], off
	v_lshl_add_u64 v[220:221], s[54:55], 0, v[128:129]
	s_add_i32 m0, s56, 0x2000
	s_nop 0
	global_load_lds_dwordx4 v[220:221], off
	v_lshl_add_u64 v[220:221], s[28:29], 0, v[134:135]
	s_mov_b32 m0, s23
	s_nop 0
	global_load_lds_dwordx4 v[220:221], off
	s_mov_b32 m0, s38
	s_nop 0
	global_load_lds_dwordx4 v[222:223], off
	s_waitcnt vmcnt(8)
	s_waitcnt lgkmcnt(0)
	s_barrier
	s_setprio 1
	s_waitcnt lgkmcnt(0)
	v_mfma_f32_16x16x32_bf16 v[60:63], v[144:147], v[182:185], v[60:63]
	v_mfma_f32_16x16x32_bf16 v[56:59], v[158:161], v[182:185], v[56:59]
	v_mfma_f32_16x16x32_bf16 v[52:55], v[144:147], v[190:193], v[52:55]
	v_mfma_f32_16x16x32_bf16 v[44:47], v[158:161], v[190:193], v[44:47]
	v_mfma_f32_16x16x32_bf16 v[36:39], v[144:147], v[198:201], v[36:39]
	v_mfma_f32_16x16x32_bf16 v[28:31], v[158:161], v[198:201], v[28:31]
	v_mfma_f32_16x16x32_bf16 v[20:23], v[144:147], v[206:209], v[20:23]
	v_mfma_f32_16x16x32_bf16 v[12:15], v[158:161], v[206:209], v[12:15]
	v_mfma_f32_16x16x32_bf16 v[60:63], v[154:157], v[186:189], v[60:63]
	v_mfma_f32_16x16x32_bf16 v[56:59], v[162:165], v[186:189], v[56:59]
	v_mfma_f32_16x16x32_bf16 v[52:55], v[154:157], v[194:197], v[52:55]
	v_mfma_f32_16x16x32_bf16 v[44:47], v[162:165], v[194:197], v[44:47]
	v_mfma_f32_16x16x32_bf16 v[36:39], v[154:157], v[202:205], v[36:39]
	v_mfma_f32_16x16x32_bf16 v[28:31], v[162:165], v[202:205], v[28:31]
	v_mfma_f32_16x16x32_bf16 v[20:23], v[154:157], v[214:217], v[20:23]
	v_mfma_f32_16x16x32_bf16 v[12:15], v[162:165], v[214:217], v[12:15]
	v_mfma_f32_16x16x32_bf16 v[48:51], v[166:169], v[182:185], v[48:51]
	v_mfma_f32_16x16x32_bf16 v[40:43], v[174:177], v[182:185], v[40:43]
	v_mfma_f32_16x16x32_bf16 v[32:35], v[166:169], v[190:193], v[32:35]
	v_mfma_f32_16x16x32_bf16 v[24:27], v[174:177], v[190:193], v[24:27]
	v_mfma_f32_16x16x32_bf16 v[16:19], v[166:169], v[198:201], v[16:19]
	v_mfma_f32_16x16x32_bf16 v[8:11], v[174:177], v[198:201], v[8:11]
	v_mfma_f32_16x16x32_bf16 v[4:7], v[166:169], v[206:209], v[4:7]
	v_mfma_f32_16x16x32_bf16 v[0:3], v[174:177], v[206:209], v[0:3]
	v_mfma_f32_16x16x32_bf16 v[48:51], v[170:173], v[186:189], v[48:51]
	v_mfma_f32_16x16x32_bf16 v[40:43], v[178:181], v[186:189], v[40:43]
	v_mfma_f32_16x16x32_bf16 v[32:35], v[170:173], v[194:197], v[32:35]
	v_mfma_f32_16x16x32_bf16 v[24:27], v[178:181], v[194:197], v[24:27]
	v_mfma_f32_16x16x32_bf16 v[16:19], v[170:173], v[202:205], v[16:19]
	v_mfma_f32_16x16x32_bf16 v[8:11], v[178:181], v[202:205], v[8:11]
	v_mfma_f32_16x16x32_bf16 v[4:7], v[170:173], v[214:217], v[4:7]
	v_mfma_f32_16x16x32_bf16 v[0:3], v[178:181], v[214:217], v[0:3]
	s_setprio 0
	s_barrier
	s_add_i32 s54, 0, 0x18000
	s_add_i32 s55, 0, 0x1c000
	v_add_u32_e32 v162, s54, v149
	v_add_u32_e32 v178, s55, v149
	ds_read_b128 v[144:147], v162
	ds_read_b128 v[154:157], v162 offset:1024
	ds_read_b128 v[158:161], v162 offset:2048
	ds_read_b128 v[162:165], v162 offset:3072
	ds_read_b128 v[166:169], v178
	ds_read_b128 v[170:173], v178 offset:1024
	ds_read_b128 v[174:177], v178 offset:2048
	ds_read_b128 v[178:181], v178 offset:3072
	s_add_u32 s28, s28, 0x80000
	s_addc_u32 s29, s29, 0
	s_mov_b32 m0, s39
	v_lshl_add_u64 v[224:225], s[28:29], 0, v[134:135]
	ds_read_b128 v[182:185], v153 offset:32768
	ds_read_b128 v[186:189], v153 offset:33792
	ds_read_b128 v[190:193], v153 offset:34816
	ds_read_b128 v[194:197], v153 offset:35840
	ds_read_b128 v[198:201], v153 offset:36864
	ds_read_b128 v[202:205], v153 offset:37888
	ds_read_b128 v[206:209], v153 offset:38912
	ds_read_b128 v[214:217], v153 offset:39936
	global_load_lds_dwordx4 v[224:225], off
	v_lshl_add_u64 v[224:225], s[28:29], 0, v[130:131]
	s_mov_b32 m0, s40
	s_nop 0
	global_load_lds_dwordx4 v[224:225], off
	s_waitcnt vmcnt(8)
	s_waitcnt lgkmcnt(0)
	s_barrier
	s_setprio 1
	s_waitcnt lgkmcnt(0)
	v_mfma_f32_16x16x32_bf16 v[124:127], v[144:147], v[182:185], v[124:127]
	v_mfma_f32_16x16x32_bf16 v[120:123], v[158:161], v[182:185], v[120:123]
	v_mfma_f32_16x16x32_bf16 v[116:119], v[144:147], v[190:193], v[116:119]
	v_mfma_f32_16x16x32_bf16 v[108:111], v[158:161], v[190:193], v[108:111]
	v_mfma_f32_16x16x32_bf16 v[100:103], v[144:147], v[198:201], v[100:103]
	v_mfma_f32_16x16x32_bf16 v[92:95], v[158:161], v[198:201], v[92:95]
	v_mfma_f32_16x16x32_bf16 v[84:87], v[144:147], v[206:209], v[84:87]
	v_mfma_f32_16x16x32_bf16 v[76:79], v[158:161], v[206:209], v[76:79]
	v_mfma_f32_16x16x32_bf16 v[124:127], v[154:157], v[186:189], v[124:127]
	v_mfma_f32_16x16x32_bf16 v[120:123], v[162:165], v[186:189], v[120:123]
	v_mfma_f32_16x16x32_bf16 v[116:119], v[154:157], v[194:197], v[116:119]
	v_mfma_f32_16x16x32_bf16 v[108:111], v[162:165], v[194:197], v[108:111]
	v_mfma_f32_16x16x32_bf16 v[100:103], v[154:157], v[202:205], v[100:103]
	v_mfma_f32_16x16x32_bf16 v[92:95], v[162:165], v[202:205], v[92:95]
	v_mfma_f32_16x16x32_bf16 v[84:87], v[154:157], v[214:217], v[84:87]
	v_mfma_f32_16x16x32_bf16 v[76:79], v[162:165], v[214:217], v[76:79]
	v_mfma_f32_16x16x32_bf16 v[112:115], v[166:169], v[182:185], v[112:115]
	v_mfma_f32_16x16x32_bf16 v[104:107], v[174:177], v[182:185], v[104:107]
	v_mfma_f32_16x16x32_bf16 v[96:99], v[166:169], v[190:193], v[96:99]
	v_mfma_f32_16x16x32_bf16 v[88:91], v[174:177], v[190:193], v[88:91]
	v_mfma_f32_16x16x32_bf16 v[80:83], v[166:169], v[198:201], v[80:83]
	v_mfma_f32_16x16x32_bf16 v[72:75], v[174:177], v[198:201], v[72:75]
	v_mfma_f32_16x16x32_bf16 v[68:71], v[166:169], v[206:209], v[68:71]
	v_mfma_f32_16x16x32_bf16 v[64:67], v[174:177], v[206:209], v[64:67]
	v_mfma_f32_16x16x32_bf16 v[112:115], v[170:173], v[186:189], v[112:115]
	v_mfma_f32_16x16x32_bf16 v[104:107], v[178:181], v[186:189], v[104:107]
	v_mfma_f32_16x16x32_bf16 v[96:99], v[170:173], v[194:197], v[96:99]
	v_mfma_f32_16x16x32_bf16 v[88:91], v[178:181], v[194:197], v[88:91]
	v_mfma_f32_16x16x32_bf16 v[80:83], v[170:173], v[202:205], v[80:83]
	v_mfma_f32_16x16x32_bf16 v[72:75], v[178:181], v[202:205], v[72:75]
	v_mfma_f32_16x16x32_bf16 v[68:71], v[170:173], v[214:217], v[68:71]
	v_mfma_f32_16x16x32_bf16 v[64:67], v[178:181], v[214:217], v[64:67]
	s_setprio 0
	s_barrier
	s_add_i32 s28, s54, s35
	v_lshl_add_u64 v[210:211], v[210:211], 0, s[10:11]
	s_mov_b32 m0, s28
	ds_read_b128 v[182:185], v153 offset:49152
	ds_read_b128 v[186:189], v153 offset:50176
	ds_read_b128 v[190:193], v153 offset:51200
	ds_read_b128 v[194:197], v153 offset:52224
	ds_read_b128 v[198:201], v153 offset:53248
	ds_read_b128 v[202:205], v153 offset:54272
	ds_read_b128 v[206:209], v153 offset:55296
	ds_read_b128 v[214:217], v153 offset:56320
	global_load_lds_dwordx4 v[210:211], off
	s_add_i32 m0, s28, 0x2000
	s_add_u32 s26, s26, 0x80080
	v_lshl_add_u64 v[210:211], v[218:219], 0, s[10:11]
	s_addc_u32 s27, s27, 0
	s_add_i32 s28, s55, s35
	global_load_lds_dwordx4 v[210:211], off
	v_lshl_add_u64 v[210:211], s[26:27], 0, v[132:133]
	s_mov_b32 m0, s28
	s_nop 0
	global_load_lds_dwordx4 v[210:211], off
	v_lshl_add_u64 v[210:211], s[26:27], 0, v[128:129]
	s_add_i32 m0, s28, 0x2000
	s_nop 0
	global_load_lds_dwordx4 v[210:211], off
	v_lshl_add_u64 v[210:211], v[220:221], 0, s[10:11]
	s_mov_b32 m0, s42
	s_nop 0
	global_load_lds_dwordx4 v[210:211], off
	v_lshl_add_u64 v[210:211], v[222:223], 0, s[10:11]
	s_mov_b32 m0, s43
	s_nop 0
	global_load_lds_dwordx4 v[210:211], off
	s_waitcnt vmcnt(8)
	s_waitcnt lgkmcnt(0)
	s_barrier
	s_setprio 1
	s_waitcnt lgkmcnt(0)
	v_mfma_f32_16x16x32_bf16 v[60:63], v[144:147], v[182:185], v[60:63]
	v_mfma_f32_16x16x32_bf16 v[56:59], v[158:161], v[182:185], v[56:59]
	v_mfma_f32_16x16x32_bf16 v[52:55], v[144:147], v[190:193], v[52:55]
	v_mfma_f32_16x16x32_bf16 v[44:47], v[158:161], v[190:193], v[44:47]
	v_mfma_f32_16x16x32_bf16 v[36:39], v[144:147], v[198:201], v[36:39]
	v_mfma_f32_16x16x32_bf16 v[28:31], v[158:161], v[198:201], v[28:31]
	v_mfma_f32_16x16x32_bf16 v[20:23], v[144:147], v[206:209], v[20:23]
	v_mfma_f32_16x16x32_bf16 v[12:15], v[158:161], v[206:209], v[12:15]
	v_mfma_f32_16x16x32_bf16 v[60:63], v[154:157], v[186:189], v[60:63]
	v_mfma_f32_16x16x32_bf16 v[56:59], v[162:165], v[186:189], v[56:59]
	v_mfma_f32_16x16x32_bf16 v[52:55], v[154:157], v[194:197], v[52:55]
	v_mfma_f32_16x16x32_bf16 v[44:47], v[162:165], v[194:197], v[44:47]
	v_mfma_f32_16x16x32_bf16 v[36:39], v[154:157], v[202:205], v[36:39]
	v_mfma_f32_16x16x32_bf16 v[28:31], v[162:165], v[202:205], v[28:31]
	v_mfma_f32_16x16x32_bf16 v[20:23], v[154:157], v[214:217], v[20:23]
	v_mfma_f32_16x16x32_bf16 v[12:15], v[162:165], v[214:217], v[12:15]
	v_mfma_f32_16x16x32_bf16 v[48:51], v[166:169], v[182:185], v[48:51]
	v_mfma_f32_16x16x32_bf16 v[40:43], v[174:177], v[182:185], v[40:43]
	v_mfma_f32_16x16x32_bf16 v[32:35], v[166:169], v[190:193], v[32:35]
	v_mfma_f32_16x16x32_bf16 v[24:27], v[174:177], v[190:193], v[24:27]
	v_mfma_f32_16x16x32_bf16 v[16:19], v[166:169], v[198:201], v[16:19]
	v_mfma_f32_16x16x32_bf16 v[8:11], v[174:177], v[198:201], v[8:11]
	v_mfma_f32_16x16x32_bf16 v[4:7], v[166:169], v[206:209], v[4:7]
	v_mfma_f32_16x16x32_bf16 v[0:3], v[174:177], v[206:209], v[0:3]
	v_mfma_f32_16x16x32_bf16 v[48:51], v[170:173], v[186:189], v[48:51]
	v_mfma_f32_16x16x32_bf16 v[40:43], v[178:181], v[186:189], v[40:43]
	v_mfma_f32_16x16x32_bf16 v[32:35], v[170:173], v[194:197], v[32:35]
	v_mfma_f32_16x16x32_bf16 v[24:27], v[178:181], v[194:197], v[24:27]
	v_mfma_f32_16x16x32_bf16 v[16:19], v[170:173], v[202:205], v[16:19]
	v_mfma_f32_16x16x32_bf16 v[8:11], v[178:181], v[202:205], v[8:11]
	v_mfma_f32_16x16x32_bf16 v[4:7], v[170:173], v[214:217], v[4:7]
	v_mfma_f32_16x16x32_bf16 v[0:3], v[178:181], v[214:217], v[0:3]
	s_setprio 0
	s_barrier
	s_add_i32 s53, s53, 2
	s_add_u32 s24, s24, 0x100
	s_addc_u32 s25, s25, 0
	s_add_u32 s51, s51, 0x100
	s_addc_u32 s52, s52, 0
	s_cmp_gt_u32 s53, 29
	s_cbranch_scc0 .LBB0_374
	s_and_b64 vcc, exec, s[12:13]
	s_cbranch_vccnz .LBB0_378
	s_cmp_gt_i32 s48, 23
	s_cbranch_scc0 .LBB0_379

.LBB0_890:
	ds_read_b128 v[144:147], v153
	ds_read_b128 v[156:159], v153 offset:1024
	ds_read_b128 v[160:163], v153 offset:2048
	ds_read_b128 v[164:167], v153 offset:3072
	ds_read_b128 v[168:171], v154
	ds_read_b128 v[172:175], v154 offset:1024
	ds_read_b128 v[176:179], v154 offset:2048
	ds_read_b128 v[180:183], v154 offset:3072
	s_add_u32 s42, s40, 0xfff80080
	s_addc_u32 s43, s41, -1
	s_cmp_eq_u32 s62, 28
	s_cselect_b32 s45, s29, s43
	s_cselect_b32 s44, s58, s42
	s_cselect_b32 s43, s27, s61
	s_cselect_b32 s42, s59, s60
	v_lshl_add_u64 v[148:149], s[40:41], 0, v[136:137]
	s_add_i32 m0, s39, 0xc000
	ds_read_b128 v[184:187], v155
	ds_read_b128 v[188:191], v155 offset:1024
	ds_read_b128 v[192:195], v155 offset:2048
	ds_read_b128 v[196:199], v155 offset:3072
	ds_read_b128 v[200:203], v155 offset:4096
	ds_read_b128 v[204:207], v155 offset:5120
	ds_read_b128 v[208:211], v155 offset:6144
	ds_read_b128 v[214:217], v155 offset:7168
	global_load_lds_dwordx4 v[148:149], off
	v_lshl_add_u64 v[148:149], s[40:41], 0, v[138:139]
	s_add_i32 m0, s39, 0xe000
	s_nop 0
	global_load_lds_dwordx4 v[148:149], off
	s_waitcnt vmcnt(8)
	s_waitcnt lgkmcnt(0)
	s_barrier
	s_setprio 1
	s_waitcnt lgkmcnt(0)
	v_mfma_f32_16x16x32_bf16 v[124:127], v[144:147], v[184:187], v[124:127]
	v_mfma_f32_16x16x32_bf16 v[120:123], v[160:163], v[184:187], v[120:123]
	v_mfma_f32_16x16x32_bf16 v[108:111], v[144:147], v[192:195], v[108:111]
	v_mfma_f32_16x16x32_bf16 v[104:107], v[160:163], v[192:195], v[104:107]
	v_mfma_f32_16x16x32_bf16 v[92:95], v[144:147], v[200:203], v[92:95]
	v_mfma_f32_16x16x32_bf16 v[88:91], v[160:163], v[200:203], v[88:91]
	v_mfma_f32_16x16x32_bf16 v[76:79], v[144:147], v[208:211], v[76:79]
	v_mfma_f32_16x16x32_bf16 v[72:75], v[160:163], v[208:211], v[72:75]
	v_mfma_f32_16x16x32_bf16 v[124:127], v[156:159], v[188:191], v[124:127]
	v_mfma_f32_16x16x32_bf16 v[120:123], v[164:167], v[188:191], v[120:123]
	v_mfma_f32_16x16x32_bf16 v[108:111], v[156:159], v[196:199], v[108:111]
	v_mfma_f32_16x16x32_bf16 v[104:107], v[164:167], v[196:199], v[104:107]
	v_mfma_f32_16x16x32_bf16 v[92:95], v[156:159], v[204:207], v[92:95]
	v_mfma_f32_16x16x32_bf16 v[88:91], v[164:167], v[204:207], v[88:91]
	v_mfma_f32_16x16x32_bf16 v[76:79], v[156:159], v[214:217], v[76:79]
	v_mfma_f32_16x16x32_bf16 v[72:75], v[164:167], v[214:217], v[72:75]
	v_mfma_f32_16x16x32_bf16 v[116:119], v[168:171], v[184:187], v[116:119]
	v_mfma_f32_16x16x32_bf16 v[112:115], v[176:179], v[184:187], v[112:115]
	v_mfma_f32_16x16x32_bf16 v[100:103], v[168:171], v[192:195], v[100:103]
	v_mfma_f32_16x16x32_bf16 v[96:99], v[176:179], v[192:195], v[96:99]
	v_mfma_f32_16x16x32_bf16 v[84:87], v[168:171], v[200:203], v[84:87]
	v_mfma_f32_16x16x32_bf16 v[80:83], v[176:179], v[200:203], v[80:83]
	v_mfma_f32_16x16x32_bf16 v[68:71], v[168:171], v[208:211], v[68:71]
	v_mfma_f32_16x16x32_bf16 v[64:67], v[176:179], v[208:211], v[64:67]
	v_mfma_f32_16x16x32_bf16 v[116:119], v[172:175], v[188:191], v[116:119]
	v_mfma_f32_16x16x32_bf16 v[112:115], v[180:183], v[188:191], v[112:115]
	v_mfma_f32_16x16x32_bf16 v[100:103], v[172:175], v[196:199], v[100:103]
	v_mfma_f32_16x16x32_bf16 v[96:99], v[180:183], v[196:199], v[96:99]
	v_mfma_f32_16x16x32_bf16 v[84:87], v[172:175], v[204:207], v[84:87]
	v_mfma_f32_16x16x32_bf16 v[80:83], v[180:183], v[204:207], v[80:83]
	v_mfma_f32_16x16x32_bf16 v[68:71], v[172:175], v[214:217], v[68:71]
	v_mfma_f32_16x16x32_bf16 v[64:67], v[180:183], v[214:217], v[64:67]
	s_setprio 0
	s_barrier
	s_add_i32 s63, s56, s47
	v_lshl_add_u64 v[148:149], s[42:43], 0, v[132:133]
	s_mov_b32 m0, s63
	ds_read_b128 v[184:187], v155 offset:16384
	ds_read_b128 v[188:191], v155 offset:17408
	ds_read_b128 v[192:195], v155 offset:18432
	ds_read_b128 v[196:199], v155 offset:19456
	ds_read_b128 v[200:203], v155 offset:20480
	ds_read_b128 v[204:207], v155 offset:21504
	ds_read_b128 v[208:211], v155 offset:22528
	ds_read_b128 v[214:217], v155 offset:23552
	global_load_lds_dwordx4 v[148:149], off
	s_add_i32 m0, s63, 0x2000
	s_add_u32 s64, s42, 0x80000
	v_lshl_add_u64 v[218:219], s[42:43], 0, v[128:129]
	s_addc_u32 s65, s43, 0
	s_add_i32 s63, s57, s47
	global_load_lds_dwordx4 v[218:219], off
	v_lshl_add_u64 v[220:221], s[64:65], 0, v[132:133]
	s_mov_b32 m0, s63
	v_lshl_add_u64 v[222:223], s[44:45], 0, v[130:131]
	global_load_lds_dwordx4 v[220:221], off
	v_lshl_add_u64 v[220:221], s[64:65], 0, v[128:129]
	s_add_i32 m0, s63, 0x2000
	s_nop 0
	global_load_lds_dwordx4 v[220:221], off
	v_lshl_add_u64 v[220:221], s[44:45], 0, v[134:135]
	s_mov_b32 m0, s39
	s_nop 0
	global_load_lds_dwordx4 v[220:221], off
	s_mov_b32 m0, s49
	s_nop 0
	global_load_lds_dwordx4 v[222:223], off
	s_waitcnt vmcnt(8)
	s_waitcnt lgkmcnt(0)
	s_barrier
	s_setprio 1
	s_waitcnt lgkmcnt(0)
	v_mfma_f32_16x16x32_bf16 v[60:63], v[144:147], v[184:187], v[60:63]
	v_mfma_f32_16x16x32_bf16 v[56:59], v[160:163], v[184:187], v[56:59]
	v_mfma_f32_16x16x32_bf16 v[44:47], v[144:147], v[192:195], v[44:47]
	v_mfma_f32_16x16x32_bf16 v[40:43], v[160:163], v[192:195], v[40:43]
	v_mfma_f32_16x16x32_bf16 v[28:31], v[144:147], v[200:203], v[28:31]
	v_mfma_f32_16x16x32_bf16 v[24:27], v[160:163], v[200:203], v[24:27]
	v_mfma_f32_16x16x32_bf16 v[12:15], v[144:147], v[208:211], v[12:15]
	v_mfma_f32_16x16x32_bf16 v[8:11], v[160:163], v[208:211], v[8:11]
	v_mfma_f32_16x16x32_bf16 v[60:63], v[156:159], v[188:191], v[60:63]
	v_mfma_f32_16x16x32_bf16 v[56:59], v[164:167], v[188:191], v[56:59]
	v_mfma_f32_16x16x32_bf16 v[44:47], v[156:159], v[196:199], v[44:47]
	v_mfma_f32_16x16x32_bf16 v[40:43], v[164:167], v[196:199], v[40:43]
	v_mfma_f32_16x16x32_bf16 v[28:31], v[156:159], v[204:207], v[28:31]
	v_mfma_f32_16x16x32_bf16 v[24:27], v[164:167], v[204:207], v[24:27]
	v_mfma_f32_16x16x32_bf16 v[12:15], v[156:159], v[214:217], v[12:15]
	v_mfma_f32_16x16x32_bf16 v[8:11], v[164:167], v[214:217], v[8:11]
	v_mfma_f32_16x16x32_bf16 v[52:55], v[168:171], v[184:187], v[52:55]
	v_mfma_f32_16x16x32_bf16 v[48:51], v[176:179], v[184:187], v[48:51]
	v_mfma_f32_16x16x32_bf16 v[36:39], v[168:171], v[192:195], v[36:39]
	v_mfma_f32_16x16x32_bf16 v[32:35], v[176:179], v[192:195], v[32:35]
	v_mfma_f32_16x16x32_bf16 v[20:23], v[168:171], v[200:203], v[20:23]
	v_mfma_f32_16x16x32_bf16 v[16:19], v[176:179], v[200:203], v[16:19]
	v_mfma_f32_16x16x32_bf16 v[4:7], v[168:171], v[208:211], v[4:7]
	v_mfma_f32_16x16x32_bf16 v[0:3], v[176:179], v[208:211], v[0:3]
	v_mfma_f32_16x16x32_bf16 v[52:55], v[172:175], v[188:191], v[52:55]
	v_mfma_f32_16x16x32_bf16 v[48:51], v[180:183], v[188:191], v[48:51]
	v_mfma_f32_16x16x32_bf16 v[36:39], v[172:175], v[196:199], v[36:39]
	v_mfma_f32_16x16x32_bf16 v[32:35], v[180:183], v[196:199], v[32:35]
	v_mfma_f32_16x16x32_bf16 v[20:23], v[172:175], v[204:207], v[20:23]
	v_mfma_f32_16x16x32_bf16 v[16:19], v[180:183], v[204:207], v[16:19]
	v_mfma_f32_16x16x32_bf16 v[4:7], v[172:175], v[214:217], v[4:7]
	v_mfma_f32_16x16x32_bf16 v[0:3], v[180:183], v[214:217], v[0:3]
	s_setprio 0
	s_barrier
	s_add_i32 s63, 0, 0x18000
	s_add_i32 s64, 0, 0x1c000
	v_add_u32_e32 v164, s63, v151
	v_add_u32_e32 v180, s64, v151
	ds_read_b128 v[144:147], v164
	ds_read_b128 v[156:159], v164 offset:1024
	ds_read_b128 v[160:163], v164 offset:2048
	ds_read_b128 v[164:167], v164 offset:3072
	ds_read_b128 v[168:171], v180
	ds_read_b128 v[172:175], v180 offset:1024
	ds_read_b128 v[176:179], v180 offset:2048
	ds_read_b128 v[180:183], v180 offset:3072
	s_add_u32 s44, s44, 0x80000
	s_addc_u32 s45, s45, 0
	s_mov_b32 m0, s50
	v_lshl_add_u64 v[224:225], s[44:45], 0, v[134:135]
	ds_read_b128 v[184:187], v155 offset:32768
	ds_read_b128 v[188:191], v155 offset:33792
	ds_read_b128 v[192:195], v155 offset:34816
	ds_read_b128 v[196:199], v155 offset:35840
	ds_read_b128 v[200:203], v155 offset:36864
	ds_read_b128 v[204:207], v155 offset:37888
	ds_read_b128 v[208:211], v155 offset:38912
	ds_read_b128 v[214:217], v155 offset:39936
	global_load_lds_dwordx4 v[224:225], off
	v_lshl_add_u64 v[224:225], s[44:45], 0, v[130:131]
	s_mov_b32 m0, s51
	s_nop 0
	global_load_lds_dwordx4 v[224:225], off
	s_waitcnt vmcnt(8)
	s_waitcnt lgkmcnt(0)
	s_barrier
	s_setprio 1
	s_waitcnt lgkmcnt(0)
	v_mfma_f32_16x16x32_bf16 v[124:127], v[144:147], v[184:187], v[124:127]
	v_mfma_f32_16x16x32_bf16 v[120:123], v[160:163], v[184:187], v[120:123]
	v_mfma_f32_16x16x32_bf16 v[108:111], v[144:147], v[192:195], v[108:111]
	v_mfma_f32_16x16x32_bf16 v[104:107], v[160:163], v[192:195], v[104:107]
	v_mfma_f32_16x16x32_bf16 v[92:95], v[144:147], v[200:203], v[92:95]
	v_mfma_f32_16x16x32_bf16 v[88:91], v[160:163], v[200:203], v[88:91]
	v_mfma_f32_16x16x32_bf16 v[76:79], v[144:147], v[208:211], v[76:79]
	v_mfma_f32_16x16x32_bf16 v[72:75], v[160:163], v[208:211], v[72:75]
	v_mfma_f32_16x16x32_bf16 v[124:127], v[156:159], v[188:191], v[124:127]
	v_mfma_f32_16x16x32_bf16 v[120:123], v[164:167], v[188:191], v[120:123]
	v_mfma_f32_16x16x32_bf16 v[108:111], v[156:159], v[196:199], v[108:111]
	v_mfma_f32_16x16x32_bf16 v[104:107], v[164:167], v[196:199], v[104:107]
	v_mfma_f32_16x16x32_bf16 v[92:95], v[156:159], v[204:207], v[92:95]
	v_mfma_f32_16x16x32_bf16 v[88:91], v[164:167], v[204:207], v[88:91]
	v_mfma_f32_16x16x32_bf16 v[76:79], v[156:159], v[214:217], v[76:79]
	v_mfma_f32_16x16x32_bf16 v[72:75], v[164:167], v[214:217], v[72:75]
	v_mfma_f32_16x16x32_bf16 v[116:119], v[168:171], v[184:187], v[116:119]
	v_mfma_f32_16x16x32_bf16 v[112:115], v[176:179], v[184:187], v[112:115]
	v_mfma_f32_16x16x32_bf16 v[100:103], v[168:171], v[192:195], v[100:103]
	v_mfma_f32_16x16x32_bf16 v[96:99], v[176:179], v[192:195], v[96:99]
	v_mfma_f32_16x16x32_bf16 v[84:87], v[168:171], v[200:203], v[84:87]
	v_mfma_f32_16x16x32_bf16 v[80:83], v[176:179], v[200:203], v[80:83]
	v_mfma_f32_16x16x32_bf16 v[68:71], v[168:171], v[208:211], v[68:71]
	v_mfma_f32_16x16x32_bf16 v[64:67], v[176:179], v[208:211], v[64:67]
	v_mfma_f32_16x16x32_bf16 v[116:119], v[172:175], v[188:191], v[116:119]
	v_mfma_f32_16x16x32_bf16 v[112:115], v[180:183], v[188:191], v[112:115]
	v_mfma_f32_16x16x32_bf16 v[100:103], v[172:175], v[196:199], v[100:103]
	v_mfma_f32_16x16x32_bf16 v[96:99], v[180:183], v[196:199], v[96:99]
	v_mfma_f32_16x16x32_bf16 v[84:87], v[172:175], v[204:207], v[84:87]
	v_mfma_f32_16x16x32_bf16 v[80:83], v[180:183], v[204:207], v[80:83]
	v_mfma_f32_16x16x32_bf16 v[68:71], v[172:175], v[214:217], v[68:71]
	v_mfma_f32_16x16x32_bf16 v[64:67], v[180:183], v[214:217], v[64:67]
	s_setprio 0
	s_barrier
	s_add_i32 s44, s63, s47
	v_lshl_add_u64 v[148:149], v[148:149], 0, s[14:15]
	s_mov_b32 m0, s44
	ds_read_b128 v[184:187], v155 offset:49152
	ds_read_b128 v[188:191], v155 offset:50176
	ds_read_b128 v[192:195], v155 offset:51200
	ds_read_b128 v[196:199], v155 offset:52224
	ds_read_b128 v[200:203], v155 offset:53248
	ds_read_b128 v[204:207], v155 offset:54272
	ds_read_b128 v[208:211], v155 offset:55296
	ds_read_b128 v[214:217], v155 offset:56320
	global_load_lds_dwordx4 v[148:149], off
	s_add_i32 m0, s44, 0x2000
	s_add_u32 s42, s42, 0x80080
	v_lshl_add_u64 v[148:149], v[218:219], 0, s[14:15]
	s_addc_u32 s43, s43, 0
	s_add_i32 s44, s64, s47
	global_load_lds_dwordx4 v[148:149], off
	v_lshl_add_u64 v[148:149], s[42:43], 0, v[132:133]
	s_mov_b32 m0, s44
	s_nop 0
	global_load_lds_dwordx4 v[148:149], off
	v_lshl_add_u64 v[148:149], s[42:43], 0, v[128:129]
	s_add_i32 m0, s44, 0x2000
	s_nop 0
	global_load_lds_dwordx4 v[148:149], off
	v_lshl_add_u64 v[148:149], v[220:221], 0, s[14:15]
	s_mov_b32 m0, s53
	s_nop 0
	global_load_lds_dwordx4 v[148:149], off
	v_lshl_add_u64 v[148:149], v[222:223], 0, s[14:15]
	s_mov_b32 m0, s54
	s_nop 0
	global_load_lds_dwordx4 v[148:149], off
	s_waitcnt vmcnt(8)
	s_waitcnt lgkmcnt(0)
	s_barrier
	s_setprio 1
	s_waitcnt lgkmcnt(0)
	v_mfma_f32_16x16x32_bf16 v[60:63], v[144:147], v[184:187], v[60:63]
	v_mfma_f32_16x16x32_bf16 v[56:59], v[160:163], v[184:187], v[56:59]
	v_mfma_f32_16x16x32_bf16 v[44:47], v[144:147], v[192:195], v[44:47]
	v_mfma_f32_16x16x32_bf16 v[40:43], v[160:163], v[192:195], v[40:43]
	v_mfma_f32_16x16x32_bf16 v[28:31], v[144:147], v[200:203], v[28:31]
	v_mfma_f32_16x16x32_bf16 v[24:27], v[160:163], v[200:203], v[24:27]
	v_mfma_f32_16x16x32_bf16 v[12:15], v[144:147], v[208:211], v[12:15]
	v_mfma_f32_16x16x32_bf16 v[8:11], v[160:163], v[208:211], v[8:11]
	v_mfma_f32_16x16x32_bf16 v[60:63], v[156:159], v[188:191], v[60:63]
	v_mfma_f32_16x16x32_bf16 v[56:59], v[164:167], v[188:191], v[56:59]
	v_mfma_f32_16x16x32_bf16 v[44:47], v[156:159], v[196:199], v[44:47]
	v_mfma_f32_16x16x32_bf16 v[40:43], v[164:167], v[196:199], v[40:43]
	v_mfma_f32_16x16x32_bf16 v[28:31], v[156:159], v[204:207], v[28:31]
	v_mfma_f32_16x16x32_bf16 v[24:27], v[164:167], v[204:207], v[24:27]
	v_mfma_f32_16x16x32_bf16 v[12:15], v[156:159], v[214:217], v[12:15]
	v_mfma_f32_16x16x32_bf16 v[8:11], v[164:167], v[214:217], v[8:11]
	v_mfma_f32_16x16x32_bf16 v[52:55], v[168:171], v[184:187], v[52:55]
	v_mfma_f32_16x16x32_bf16 v[48:51], v[176:179], v[184:187], v[48:51]
	v_mfma_f32_16x16x32_bf16 v[36:39], v[168:171], v[192:195], v[36:39]
	v_mfma_f32_16x16x32_bf16 v[32:35], v[176:179], v[192:195], v[32:35]
	v_mfma_f32_16x16x32_bf16 v[20:23], v[168:171], v[200:203], v[20:23]
	v_mfma_f32_16x16x32_bf16 v[16:19], v[176:179], v[200:203], v[16:19]
	v_mfma_f32_16x16x32_bf16 v[4:7], v[168:171], v[208:211], v[4:7]
	v_mfma_f32_16x16x32_bf16 v[0:3], v[176:179], v[208:211], v[0:3]
	v_mfma_f32_16x16x32_bf16 v[52:55], v[172:175], v[188:191], v[52:55]
	v_mfma_f32_16x16x32_bf16 v[48:51], v[180:183], v[188:191], v[48:51]
	v_mfma_f32_16x16x32_bf16 v[36:39], v[172:175], v[196:199], v[36:39]
	v_mfma_f32_16x16x32_bf16 v[32:35], v[180:183], v[196:199], v[32:35]
	v_mfma_f32_16x16x32_bf16 v[20:23], v[172:175], v[204:207], v[20:23]
	v_mfma_f32_16x16x32_bf16 v[16:19], v[180:183], v[204:207], v[16:19]
	v_mfma_f32_16x16x32_bf16 v[4:7], v[172:175], v[214:217], v[4:7]
	v_mfma_f32_16x16x32_bf16 v[0:3], v[180:183], v[214:217], v[0:3]
	s_setprio 0
	s_barrier
	s_add_i32 s62, s62, 2
	s_add_u32 s40, s40, 0x100
	s_addc_u32 s41, s41, 0
	s_add_u32 s60, s60, 0x100
	s_addc_u32 s61, s61, 0
	s_cmp_gt_u32 s62, 29
	s_cbranch_scc0 .LBB0_890
	s_and_b64 vcc, exec, s[16:17]
	s_cbranch_vccz .LBB0_893
	s_barrier

.LBB0_1023:
	ds_read_b128 v[152:155], v149
	ds_read_b128 v[156:159], v149 offset:1024
	ds_read_b128 v[160:163], v149 offset:2048
	ds_read_b128 v[164:167], v149 offset:3072
	ds_read_b128 v[168:171], v150
	ds_read_b128 v[172:175], v150 offset:1024
	ds_read_b128 v[176:179], v150 offset:2048
	ds_read_b128 v[180:183], v150 offset:3072
	s_add_u32 s26, s24, 0xfff80080
	s_addc_u32 s27, s25, -1
	s_cmp_eq_u32 s53, 28
	s_cselect_b32 s29, s17, s27
	s_cselect_b32 s28, s49, s26
	s_cselect_b32 s27, s15, s52
	s_cselect_b32 s26, s50, s51
	v_lshl_add_u64 v[144:145], s[24:25], 0, v[136:137]
	s_add_i32 m0, s23, 0xc000
	ds_read_b128 v[184:187], v151
	ds_read_b128 v[188:191], v151 offset:1024
	ds_read_b128 v[192:195], v151 offset:2048
	ds_read_b128 v[196:199], v151 offset:3072
	ds_read_b128 v[200:203], v151 offset:4096
	ds_read_b128 v[204:207], v151 offset:5120
	ds_read_b128 v[208:211], v151 offset:6144
	ds_read_b128 v[214:217], v151 offset:7168
	global_load_lds_dwordx4 v[144:145], off
	v_lshl_add_u64 v[144:145], s[24:25], 0, v[138:139]
	s_add_i32 m0, s23, 0xe000
	s_nop 0
	global_load_lds_dwordx4 v[144:145], off
	s_waitcnt vmcnt(8)
	s_waitcnt lgkmcnt(0)
	s_barrier
	s_setprio 1
	s_waitcnt lgkmcnt(0)
	v_mfma_f32_16x16x32_bf16 v[124:127], v[152:155], v[184:187], v[124:127]
	v_mfma_f32_16x16x32_bf16 v[120:123], v[160:163], v[184:187], v[120:123]
	v_mfma_f32_16x16x32_bf16 v[108:111], v[152:155], v[192:195], v[108:111]
	v_mfma_f32_16x16x32_bf16 v[104:107], v[160:163], v[192:195], v[104:107]
	v_mfma_f32_16x16x32_bf16 v[92:95], v[152:155], v[200:203], v[92:95]
	v_mfma_f32_16x16x32_bf16 v[88:91], v[160:163], v[200:203], v[88:91]
	v_mfma_f32_16x16x32_bf16 v[76:79], v[152:155], v[208:211], v[76:79]
	v_mfma_f32_16x16x32_bf16 v[72:75], v[160:163], v[208:211], v[72:75]
	v_mfma_f32_16x16x32_bf16 v[124:127], v[156:159], v[188:191], v[124:127]
	v_mfma_f32_16x16x32_bf16 v[120:123], v[164:167], v[188:191], v[120:123]
	v_mfma_f32_16x16x32_bf16 v[108:111], v[156:159], v[196:199], v[108:111]
	v_mfma_f32_16x16x32_bf16 v[104:107], v[164:167], v[196:199], v[104:107]
	v_mfma_f32_16x16x32_bf16 v[92:95], v[156:159], v[204:207], v[92:95]
	v_mfma_f32_16x16x32_bf16 v[88:91], v[164:167], v[204:207], v[88:91]
	v_mfma_f32_16x16x32_bf16 v[76:79], v[156:159], v[214:217], v[76:79]
	v_mfma_f32_16x16x32_bf16 v[72:75], v[164:167], v[214:217], v[72:75]
	v_mfma_f32_16x16x32_bf16 v[116:119], v[168:171], v[184:187], v[116:119]
	v_mfma_f32_16x16x32_bf16 v[112:115], v[176:179], v[184:187], v[112:115]
	v_mfma_f32_16x16x32_bf16 v[100:103], v[168:171], v[192:195], v[100:103]
	v_mfma_f32_16x16x32_bf16 v[96:99], v[176:179], v[192:195], v[96:99]
	v_mfma_f32_16x16x32_bf16 v[84:87], v[168:171], v[200:203], v[84:87]
	v_mfma_f32_16x16x32_bf16 v[80:83], v[176:179], v[200:203], v[80:83]
	v_mfma_f32_16x16x32_bf16 v[68:71], v[168:171], v[208:211], v[68:71]
	v_mfma_f32_16x16x32_bf16 v[64:67], v[176:179], v[208:211], v[64:67]
	v_mfma_f32_16x16x32_bf16 v[116:119], v[172:175], v[188:191], v[116:119]
	v_mfma_f32_16x16x32_bf16 v[112:115], v[180:183], v[188:191], v[112:115]
	v_mfma_f32_16x16x32_bf16 v[100:103], v[172:175], v[196:199], v[100:103]
	v_mfma_f32_16x16x32_bf16 v[96:99], v[180:183], v[196:199], v[96:99]
	v_mfma_f32_16x16x32_bf16 v[84:87], v[172:175], v[204:207], v[84:87]
	v_mfma_f32_16x16x32_bf16 v[80:83], v[180:183], v[204:207], v[80:83]
	v_mfma_f32_16x16x32_bf16 v[68:71], v[172:175], v[214:217], v[68:71]
	v_mfma_f32_16x16x32_bf16 v[64:67], v[180:183], v[214:217], v[64:67]
	s_setprio 0
	s_barrier
	s_add_i32 s54, s45, s36
	v_lshl_add_u64 v[144:145], s[26:27], 0, v[132:133]
	s_mov_b32 m0, s54
	ds_read_b128 v[184:187], v151 offset:16384
	ds_read_b128 v[188:191], v151 offset:17408
	ds_read_b128 v[192:195], v151 offset:18432
	ds_read_b128 v[196:199], v151 offset:19456
	ds_read_b128 v[200:203], v151 offset:20480
	ds_read_b128 v[204:207], v151 offset:21504
	ds_read_b128 v[208:211], v151 offset:22528
	ds_read_b128 v[214:217], v151 offset:23552
	global_load_lds_dwordx4 v[144:145], off
	s_add_i32 m0, s54, 0x2000
	s_add_u32 s54, s26, 0x80000
	v_lshl_add_u64 v[218:219], s[26:27], 0, v[128:129]
	s_addc_u32 s55, s27, 0
	s_add_i32 s56, s46, s36
	global_load_lds_dwordx4 v[218:219], off
	v_lshl_add_u64 v[220:221], s[54:55], 0, v[132:133]
	s_mov_b32 m0, s56
	v_lshl_add_u64 v[222:223], s[28:29], 0, v[130:131]
	global_load_lds_dwordx4 v[220:221], off
	v_lshl_add_u64 v[220:221], s[54:55], 0, v[128:129]
	s_add_i32 m0, s56, 0x2000
	s_nop 0
	global_load_lds_dwordx4 v[220:221], off
	v_lshl_add_u64 v[220:221], s[28:29], 0, v[134:135]
	s_mov_b32 m0, s23
	s_nop 0
	global_load_lds_dwordx4 v[220:221], off
	s_mov_b32 m0, s39
	s_nop 0
	global_load_lds_dwordx4 v[222:223], off
	s_waitcnt vmcnt(8)
	s_waitcnt lgkmcnt(0)
	s_barrier
	s_setprio 1
	s_waitcnt lgkmcnt(0)
	v_mfma_f32_16x16x32_bf16 v[60:63], v[152:155], v[184:187], v[60:63]
	v_mfma_f32_16x16x32_bf16 v[56:59], v[160:163], v[184:187], v[56:59]
	v_mfma_f32_16x16x32_bf16 v[44:47], v[152:155], v[192:195], v[44:47]
	v_mfma_f32_16x16x32_bf16 v[40:43], v[160:163], v[192:195], v[40:43]
	v_mfma_f32_16x16x32_bf16 v[28:31], v[152:155], v[200:203], v[28:31]
	v_mfma_f32_16x16x32_bf16 v[24:27], v[160:163], v[200:203], v[24:27]
	v_mfma_f32_16x16x32_bf16 v[12:15], v[152:155], v[208:211], v[12:15]
	v_mfma_f32_16x16x32_bf16 v[8:11], v[160:163], v[208:211], v[8:11]
	v_mfma_f32_16x16x32_bf16 v[60:63], v[156:159], v[188:191], v[60:63]
	v_mfma_f32_16x16x32_bf16 v[56:59], v[164:167], v[188:191], v[56:59]
	v_mfma_f32_16x16x32_bf16 v[44:47], v[156:159], v[196:199], v[44:47]
	v_mfma_f32_16x16x32_bf16 v[40:43], v[164:167], v[196:199], v[40:43]
	v_mfma_f32_16x16x32_bf16 v[28:31], v[156:159], v[204:207], v[28:31]
	v_mfma_f32_16x16x32_bf16 v[24:27], v[164:167], v[204:207], v[24:27]
	v_mfma_f32_16x16x32_bf16 v[12:15], v[156:159], v[214:217], v[12:15]
	v_mfma_f32_16x16x32_bf16 v[8:11], v[164:167], v[214:217], v[8:11]
	v_mfma_f32_16x16x32_bf16 v[52:55], v[168:171], v[184:187], v[52:55]
	v_mfma_f32_16x16x32_bf16 v[48:51], v[176:179], v[184:187], v[48:51]
	v_mfma_f32_16x16x32_bf16 v[36:39], v[168:171], v[192:195], v[36:39]
	v_mfma_f32_16x16x32_bf16 v[32:35], v[176:179], v[192:195], v[32:35]
	v_mfma_f32_16x16x32_bf16 v[20:23], v[168:171], v[200:203], v[20:23]
	v_mfma_f32_16x16x32_bf16 v[16:19], v[176:179], v[200:203], v[16:19]
	v_mfma_f32_16x16x32_bf16 v[4:7], v[168:171], v[208:211], v[4:7]
	v_mfma_f32_16x16x32_bf16 v[0:3], v[176:179], v[208:211], v[0:3]
	v_mfma_f32_16x16x32_bf16 v[52:55], v[172:175], v[188:191], v[52:55]
	v_mfma_f32_16x16x32_bf16 v[48:51], v[180:183], v[188:191], v[48:51]
	v_mfma_f32_16x16x32_bf16 v[36:39], v[172:175], v[196:199], v[36:39]
	v_mfma_f32_16x16x32_bf16 v[32:35], v[180:183], v[196:199], v[32:35]
	v_mfma_f32_16x16x32_bf16 v[20:23], v[172:175], v[204:207], v[20:23]
	v_mfma_f32_16x16x32_bf16 v[16:19], v[180:183], v[204:207], v[16:19]
	v_mfma_f32_16x16x32_bf16 v[4:7], v[172:175], v[214:217], v[4:7]
	v_mfma_f32_16x16x32_bf16 v[0:3], v[180:183], v[214:217], v[0:3]
	s_setprio 0
	s_barrier
	s_add_i32 s54, 0, 0x18000
	s_add_i32 s55, 0, 0x1c000
	v_add_u32_e32 v164, s54, v147
	v_add_u32_e32 v180, s55, v147
	ds_read_b128 v[152:155], v164
	ds_read_b128 v[156:159], v164 offset:1024
	ds_read_b128 v[160:163], v164 offset:2048
	ds_read_b128 v[164:167], v164 offset:3072
	ds_read_b128 v[168:171], v180
	ds_read_b128 v[172:175], v180 offset:1024
	ds_read_b128 v[176:179], v180 offset:2048
	ds_read_b128 v[180:183], v180 offset:3072
	s_add_u32 s28, s28, 0x80000
	s_addc_u32 s29, s29, 0
	s_mov_b32 m0, s40
	v_lshl_add_u64 v[224:225], s[28:29], 0, v[134:135]
	ds_read_b128 v[184:187], v151 offset:32768
	ds_read_b128 v[188:191], v151 offset:33792
	ds_read_b128 v[192:195], v151 offset:34816
	ds_read_b128 v[196:199], v151 offset:35840
	ds_read_b128 v[200:203], v151 offset:36864
	ds_read_b128 v[204:207], v151 offset:37888
	ds_read_b128 v[208:211], v151 offset:38912
	ds_read_b128 v[214:217], v151 offset:39936
	global_load_lds_dwordx4 v[224:225], off
	v_lshl_add_u64 v[224:225], s[28:29], 0, v[130:131]
	s_mov_b32 m0, s41
	s_nop 0
	global_load_lds_dwordx4 v[224:225], off
	s_waitcnt vmcnt(8)
	s_waitcnt lgkmcnt(0)
	s_barrier
	s_setprio 1
	s_waitcnt lgkmcnt(0)
	v_mfma_f32_16x16x32_bf16 v[124:127], v[152:155], v[184:187], v[124:127]
	v_mfma_f32_16x16x32_bf16 v[120:123], v[160:163], v[184:187], v[120:123]
	v_mfma_f32_16x16x32_bf16 v[108:111], v[152:155], v[192:195], v[108:111]
	v_mfma_f32_16x16x32_bf16 v[104:107], v[160:163], v[192:195], v[104:107]
	v_mfma_f32_16x16x32_bf16 v[92:95], v[152:155], v[200:203], v[92:95]
	v_mfma_f32_16x16x32_bf16 v[88:91], v[160:163], v[200:203], v[88:91]
	v_mfma_f32_16x16x32_bf16 v[76:79], v[152:155], v[208:211], v[76:79]
	v_mfma_f32_16x16x32_bf16 v[72:75], v[160:163], v[208:211], v[72:75]
	v_mfma_f32_16x16x32_bf16 v[124:127], v[156:159], v[188:191], v[124:127]
	v_mfma_f32_16x16x32_bf16 v[120:123], v[164:167], v[188:191], v[120:123]
	v_mfma_f32_16x16x32_bf16 v[108:111], v[156:159], v[196:199], v[108:111]
	v_mfma_f32_16x16x32_bf16 v[104:107], v[164:167], v[196:199], v[104:107]
	v_mfma_f32_16x16x32_bf16 v[92:95], v[156:159], v[204:207], v[92:95]
	v_mfma_f32_16x16x32_bf16 v[88:91], v[164:167], v[204:207], v[88:91]
	v_mfma_f32_16x16x32_bf16 v[76:79], v[156:159], v[214:217], v[76:79]
	v_mfma_f32_16x16x32_bf16 v[72:75], v[164:167], v[214:217], v[72:75]
	v_mfma_f32_16x16x32_bf16 v[116:119], v[168:171], v[184:187], v[116:119]
	v_mfma_f32_16x16x32_bf16 v[112:115], v[176:179], v[184:187], v[112:115]
	v_mfma_f32_16x16x32_bf16 v[100:103], v[168:171], v[192:195], v[100:103]
	v_mfma_f32_16x16x32_bf16 v[96:99], v[176:179], v[192:195], v[96:99]
	v_mfma_f32_16x16x32_bf16 v[84:87], v[168:171], v[200:203], v[84:87]
	v_mfma_f32_16x16x32_bf16 v[80:83], v[176:179], v[200:203], v[80:83]
	v_mfma_f32_16x16x32_bf16 v[68:71], v[168:171], v[208:211], v[68:71]
	v_mfma_f32_16x16x32_bf16 v[64:67], v[176:179], v[208:211], v[64:67]
	v_mfma_f32_16x16x32_bf16 v[116:119], v[172:175], v[188:191], v[116:119]
	v_mfma_f32_16x16x32_bf16 v[112:115], v[180:183], v[188:191], v[112:115]
	v_mfma_f32_16x16x32_bf16 v[100:103], v[172:175], v[196:199], v[100:103]
	v_mfma_f32_16x16x32_bf16 v[96:99], v[180:183], v[196:199], v[96:99]
	v_mfma_f32_16x16x32_bf16 v[84:87], v[172:175], v[204:207], v[84:87]
	v_mfma_f32_16x16x32_bf16 v[80:83], v[180:183], v[204:207], v[80:83]
	v_mfma_f32_16x16x32_bf16 v[68:71], v[172:175], v[214:217], v[68:71]
	v_mfma_f32_16x16x32_bf16 v[64:67], v[180:183], v[214:217], v[64:67]
	s_setprio 0
	s_barrier
	s_add_i32 s28, s54, s36
	v_lshl_add_u64 v[144:145], v[144:145], 0, s[10:11]
	s_mov_b32 m0, s28
	ds_read_b128 v[184:187], v151 offset:49152
	ds_read_b128 v[188:191], v151 offset:50176
	ds_read_b128 v[192:195], v151 offset:51200
	ds_read_b128 v[196:199], v151 offset:52224
	ds_read_b128 v[200:203], v151 offset:53248
	ds_read_b128 v[204:207], v151 offset:54272
	ds_read_b128 v[208:211], v151 offset:55296
	ds_read_b128 v[214:217], v151 offset:56320
	global_load_lds_dwordx4 v[144:145], off
	s_add_i32 m0, s28, 0x2000
	s_add_u32 s26, s26, 0x80080
	v_lshl_add_u64 v[144:145], v[218:219], 0, s[10:11]
	s_addc_u32 s27, s27, 0
	s_add_i32 s28, s55, s36
	global_load_lds_dwordx4 v[144:145], off
	v_lshl_add_u64 v[144:145], s[26:27], 0, v[132:133]
	s_mov_b32 m0, s28
	s_nop 0
	global_load_lds_dwordx4 v[144:145], off
	v_lshl_add_u64 v[144:145], s[26:27], 0, v[128:129]
	s_add_i32 m0, s28, 0x2000
	s_nop 0
	global_load_lds_dwordx4 v[144:145], off
	v_lshl_add_u64 v[144:145], v[220:221], 0, s[10:11]
	s_mov_b32 m0, s33
	s_nop 0
	global_load_lds_dwordx4 v[144:145], off
	v_lshl_add_u64 v[144:145], v[222:223], 0, s[10:11]
	s_mov_b32 m0, s43
	s_nop 0
	global_load_lds_dwordx4 v[144:145], off
	s_waitcnt vmcnt(8)
	s_waitcnt lgkmcnt(0)
	s_barrier
	s_setprio 1
	s_waitcnt lgkmcnt(0)
	v_mfma_f32_16x16x32_bf16 v[60:63], v[152:155], v[184:187], v[60:63]
	v_mfma_f32_16x16x32_bf16 v[56:59], v[160:163], v[184:187], v[56:59]
	v_mfma_f32_16x16x32_bf16 v[44:47], v[152:155], v[192:195], v[44:47]
	v_mfma_f32_16x16x32_bf16 v[40:43], v[160:163], v[192:195], v[40:43]
	v_mfma_f32_16x16x32_bf16 v[28:31], v[152:155], v[200:203], v[28:31]
	v_mfma_f32_16x16x32_bf16 v[24:27], v[160:163], v[200:203], v[24:27]
	v_mfma_f32_16x16x32_bf16 v[12:15], v[152:155], v[208:211], v[12:15]
	v_mfma_f32_16x16x32_bf16 v[8:11], v[160:163], v[208:211], v[8:11]
	v_mfma_f32_16x16x32_bf16 v[60:63], v[156:159], v[188:191], v[60:63]
	v_mfma_f32_16x16x32_bf16 v[56:59], v[164:167], v[188:191], v[56:59]
	v_mfma_f32_16x16x32_bf16 v[44:47], v[156:159], v[196:199], v[44:47]
	v_mfma_f32_16x16x32_bf16 v[40:43], v[164:167], v[196:199], v[40:43]
	v_mfma_f32_16x16x32_bf16 v[28:31], v[156:159], v[204:207], v[28:31]
	v_mfma_f32_16x16x32_bf16 v[24:27], v[164:167], v[204:207], v[24:27]
	v_mfma_f32_16x16x32_bf16 v[12:15], v[156:159], v[214:217], v[12:15]
	v_mfma_f32_16x16x32_bf16 v[8:11], v[164:167], v[214:217], v[8:11]
	v_mfma_f32_16x16x32_bf16 v[52:55], v[168:171], v[184:187], v[52:55]
	v_mfma_f32_16x16x32_bf16 v[48:51], v[176:179], v[184:187], v[48:51]
	v_mfma_f32_16x16x32_bf16 v[36:39], v[168:171], v[192:195], v[36:39]
	v_mfma_f32_16x16x32_bf16 v[32:35], v[176:179], v[192:195], v[32:35]
	v_mfma_f32_16x16x32_bf16 v[20:23], v[168:171], v[200:203], v[20:23]
	v_mfma_f32_16x16x32_bf16 v[16:19], v[176:179], v[200:203], v[16:19]
	v_mfma_f32_16x16x32_bf16 v[4:7], v[168:171], v[208:211], v[4:7]
	v_mfma_f32_16x16x32_bf16 v[0:3], v[176:179], v[208:211], v[0:3]
	v_mfma_f32_16x16x32_bf16 v[52:55], v[172:175], v[188:191], v[52:55]
	v_mfma_f32_16x16x32_bf16 v[48:51], v[180:183], v[188:191], v[48:51]
	v_mfma_f32_16x16x32_bf16 v[36:39], v[172:175], v[196:199], v[36:39]
	v_mfma_f32_16x16x32_bf16 v[32:35], v[180:183], v[196:199], v[32:35]
	v_mfma_f32_16x16x32_bf16 v[20:23], v[172:175], v[204:207], v[20:23]
	v_mfma_f32_16x16x32_bf16 v[16:19], v[180:183], v[204:207], v[16:19]
	v_mfma_f32_16x16x32_bf16 v[4:7], v[172:175], v[214:217], v[4:7]
	v_mfma_f32_16x16x32_bf16 v[0:3], v[180:183], v[214:217], v[0:3]
	s_setprio 0
	s_barrier
	s_add_i32 s53, s53, 2
	s_add_u32 s24, s24, 0x100
	s_addc_u32 s25, s25, 0
	s_add_u32 s51, s51, 0x100
	s_addc_u32 s52, s52, 0
	s_cmp_gt_u32 s53, 29
	s_cbranch_scc0 .LBB0_1023
	s_and_b64 vcc, exec, s[12:13]
	s_cbranch_vccz .LBB0_1026
	s_barrier

.LBB0_1241:
	ds_read_b128 v[144:147], v153
	ds_read_b128 v[156:159], v153 offset:1024
	ds_read_b128 v[160:163], v153 offset:2048
	ds_read_b128 v[164:167], v153 offset:3072
	ds_read_b128 v[168:171], v154
	ds_read_b128 v[172:175], v154 offset:1024
	ds_read_b128 v[176:179], v154 offset:2048
	ds_read_b128 v[180:183], v154 offset:3072
	s_add_u32 s50, s48, 0xfff80080
	s_addc_u32 s51, s49, -1
	s_cmp_eq_u32 s73, 28
	s_cselect_b32 s53, s41, s51
	s_cselect_b32 s52, s67, s50
	s_cselect_b32 s51, s39, s72
	s_cselect_b32 s50, s70, s71
	v_lshl_add_u64 v[148:149], s[48:49], 0, v[136:137]
	s_add_i32 m0, s47, 0xc000
	ds_read_b128 v[184:187], v155
	ds_read_b128 v[188:191], v155 offset:1024
	ds_read_b128 v[192:195], v155 offset:2048
	ds_read_b128 v[196:199], v155 offset:3072
	ds_read_b128 v[200:203], v155 offset:4096
	ds_read_b128 v[204:207], v155 offset:5120
	ds_read_b128 v[208:211], v155 offset:6144
	ds_read_b128 v[214:217], v155 offset:7168
	global_load_lds_dwordx4 v[148:149], off
	v_lshl_add_u64 v[148:149], s[48:49], 0, v[138:139]
	s_add_i32 m0, s47, 0xe000
	s_nop 0
	global_load_lds_dwordx4 v[148:149], off
	s_waitcnt vmcnt(8)
	s_waitcnt lgkmcnt(0)
	s_barrier
	s_setprio 1
	s_waitcnt lgkmcnt(0)
	v_mfma_f32_16x16x32_bf16 v[124:127], v[144:147], v[184:187], v[124:127]
	v_mfma_f32_16x16x32_bf16 v[120:123], v[160:163], v[184:187], v[120:123]
	v_mfma_f32_16x16x32_bf16 v[108:111], v[144:147], v[192:195], v[108:111]
	v_mfma_f32_16x16x32_bf16 v[104:107], v[160:163], v[192:195], v[104:107]
	v_mfma_f32_16x16x32_bf16 v[92:95], v[144:147], v[200:203], v[92:95]
	v_mfma_f32_16x16x32_bf16 v[88:91], v[160:163], v[200:203], v[88:91]
	v_mfma_f32_16x16x32_bf16 v[76:79], v[144:147], v[208:211], v[76:79]
	v_mfma_f32_16x16x32_bf16 v[72:75], v[160:163], v[208:211], v[72:75]
	v_mfma_f32_16x16x32_bf16 v[124:127], v[156:159], v[188:191], v[124:127]
	v_mfma_f32_16x16x32_bf16 v[120:123], v[164:167], v[188:191], v[120:123]
	v_mfma_f32_16x16x32_bf16 v[108:111], v[156:159], v[196:199], v[108:111]
	v_mfma_f32_16x16x32_bf16 v[104:107], v[164:167], v[196:199], v[104:107]
	v_mfma_f32_16x16x32_bf16 v[92:95], v[156:159], v[204:207], v[92:95]
	v_mfma_f32_16x16x32_bf16 v[88:91], v[164:167], v[204:207], v[88:91]
	v_mfma_f32_16x16x32_bf16 v[76:79], v[156:159], v[214:217], v[76:79]
	v_mfma_f32_16x16x32_bf16 v[72:75], v[164:167], v[214:217], v[72:75]
	v_mfma_f32_16x16x32_bf16 v[116:119], v[168:171], v[184:187], v[116:119]
	v_mfma_f32_16x16x32_bf16 v[112:115], v[176:179], v[184:187], v[112:115]
	v_mfma_f32_16x16x32_bf16 v[100:103], v[168:171], v[192:195], v[100:103]
	v_mfma_f32_16x16x32_bf16 v[96:99], v[176:179], v[192:195], v[96:99]
	v_mfma_f32_16x16x32_bf16 v[84:87], v[168:171], v[200:203], v[84:87]
	v_mfma_f32_16x16x32_bf16 v[80:83], v[176:179], v[200:203], v[80:83]
	v_mfma_f32_16x16x32_bf16 v[68:71], v[168:171], v[208:211], v[68:71]
	v_mfma_f32_16x16x32_bf16 v[64:67], v[176:179], v[208:211], v[64:67]
	v_mfma_f32_16x16x32_bf16 v[116:119], v[172:175], v[188:191], v[116:119]
	v_mfma_f32_16x16x32_bf16 v[112:115], v[180:183], v[188:191], v[112:115]
	v_mfma_f32_16x16x32_bf16 v[100:103], v[172:175], v[196:199], v[100:103]
	v_mfma_f32_16x16x32_bf16 v[96:99], v[180:183], v[196:199], v[96:99]
	v_mfma_f32_16x16x32_bf16 v[84:87], v[172:175], v[204:207], v[84:87]
	v_mfma_f32_16x16x32_bf16 v[80:83], v[180:183], v[204:207], v[80:83]
	v_mfma_f32_16x16x32_bf16 v[68:71], v[172:175], v[214:217], v[68:71]
	v_mfma_f32_16x16x32_bf16 v[64:67], v[180:183], v[214:217], v[64:67]
	s_setprio 0
	s_barrier
	s_add_i32 s74, s65, s56
	v_lshl_add_u64 v[148:149], s[50:51], 0, v[132:133]
	s_mov_b32 m0, s74
	ds_read_b128 v[184:187], v155 offset:16384
	ds_read_b128 v[188:191], v155 offset:17408
	ds_read_b128 v[192:195], v155 offset:18432
	ds_read_b128 v[196:199], v155 offset:19456
	ds_read_b128 v[200:203], v155 offset:20480
	ds_read_b128 v[204:207], v155 offset:21504
	ds_read_b128 v[208:211], v155 offset:22528
	ds_read_b128 v[214:217], v155 offset:23552
	global_load_lds_dwordx4 v[148:149], off
	s_add_i32 m0, s74, 0x2000
	s_add_u32 s74, s50, 0x80000
	v_lshl_add_u64 v[218:219], s[50:51], 0, v[128:129]
	s_addc_u32 s75, s51, 0
	s_add_i32 s76, s66, s56
	global_load_lds_dwordx4 v[218:219], off
	v_lshl_add_u64 v[220:221], s[74:75], 0, v[132:133]
	s_mov_b32 m0, s76
	v_lshl_add_u64 v[222:223], s[52:53], 0, v[130:131]
	global_load_lds_dwordx4 v[220:221], off
	v_lshl_add_u64 v[220:221], s[74:75], 0, v[128:129]
	s_add_i32 m0, s76, 0x2000
	s_nop 0
	global_load_lds_dwordx4 v[220:221], off
	v_lshl_add_u64 v[220:221], s[52:53], 0, v[134:135]
	s_mov_b32 m0, s47
	s_nop 0
	global_load_lds_dwordx4 v[220:221], off
	s_mov_b32 m0, s58
	s_nop 0
	global_load_lds_dwordx4 v[222:223], off
	s_waitcnt vmcnt(8)
	s_waitcnt lgkmcnt(0)
	s_barrier
	s_setprio 1
	s_waitcnt lgkmcnt(0)
	v_mfma_f32_16x16x32_bf16 v[60:63], v[144:147], v[184:187], v[60:63]
	v_mfma_f32_16x16x32_bf16 v[56:59], v[160:163], v[184:187], v[56:59]
	v_mfma_f32_16x16x32_bf16 v[44:47], v[144:147], v[192:195], v[44:47]
	v_mfma_f32_16x16x32_bf16 v[40:43], v[160:163], v[192:195], v[40:43]
	v_mfma_f32_16x16x32_bf16 v[28:31], v[144:147], v[200:203], v[28:31]
	v_mfma_f32_16x16x32_bf16 v[24:27], v[160:163], v[200:203], v[24:27]
	v_mfma_f32_16x16x32_bf16 v[12:15], v[144:147], v[208:211], v[12:15]
	v_mfma_f32_16x16x32_bf16 v[8:11], v[160:163], v[208:211], v[8:11]
	v_mfma_f32_16x16x32_bf16 v[60:63], v[156:159], v[188:191], v[60:63]
	v_mfma_f32_16x16x32_bf16 v[56:59], v[164:167], v[188:191], v[56:59]
	v_mfma_f32_16x16x32_bf16 v[44:47], v[156:159], v[196:199], v[44:47]
	v_mfma_f32_16x16x32_bf16 v[40:43], v[164:167], v[196:199], v[40:43]
	v_mfma_f32_16x16x32_bf16 v[28:31], v[156:159], v[204:207], v[28:31]
	v_mfma_f32_16x16x32_bf16 v[24:27], v[164:167], v[204:207], v[24:27]
	v_mfma_f32_16x16x32_bf16 v[12:15], v[156:159], v[214:217], v[12:15]
	v_mfma_f32_16x16x32_bf16 v[8:11], v[164:167], v[214:217], v[8:11]
	v_mfma_f32_16x16x32_bf16 v[52:55], v[168:171], v[184:187], v[52:55]
	v_mfma_f32_16x16x32_bf16 v[48:51], v[176:179], v[184:187], v[48:51]
	v_mfma_f32_16x16x32_bf16 v[36:39], v[168:171], v[192:195], v[36:39]
	v_mfma_f32_16x16x32_bf16 v[32:35], v[176:179], v[192:195], v[32:35]
	v_mfma_f32_16x16x32_bf16 v[20:23], v[168:171], v[200:203], v[20:23]
	v_mfma_f32_16x16x32_bf16 v[16:19], v[176:179], v[200:203], v[16:19]
	v_mfma_f32_16x16x32_bf16 v[4:7], v[168:171], v[208:211], v[4:7]
	v_mfma_f32_16x16x32_bf16 v[0:3], v[176:179], v[208:211], v[0:3]
	v_mfma_f32_16x16x32_bf16 v[52:55], v[172:175], v[188:191], v[52:55]
	v_mfma_f32_16x16x32_bf16 v[48:51], v[180:183], v[188:191], v[48:51]
	v_mfma_f32_16x16x32_bf16 v[36:39], v[172:175], v[196:199], v[36:39]
	v_mfma_f32_16x16x32_bf16 v[32:35], v[180:183], v[196:199], v[32:35]
	v_mfma_f32_16x16x32_bf16 v[20:23], v[172:175], v[204:207], v[20:23]
	v_mfma_f32_16x16x32_bf16 v[16:19], v[180:183], v[204:207], v[16:19]
	v_mfma_f32_16x16x32_bf16 v[4:7], v[172:175], v[214:217], v[4:7]
	v_mfma_f32_16x16x32_bf16 v[0:3], v[180:183], v[214:217], v[0:3]
	s_setprio 0
	s_barrier
	s_add_i32 s74, 0, 0x18000
	s_add_i32 s75, 0, 0x1c000
	v_add_u32_e32 v164, s74, v151
	v_add_u32_e32 v180, s75, v151
	ds_read_b128 v[144:147], v164
	ds_read_b128 v[156:159], v164 offset:1024
	ds_read_b128 v[160:163], v164 offset:2048
	ds_read_b128 v[164:167], v164 offset:3072
	ds_read_b128 v[168:171], v180
	ds_read_b128 v[172:175], v180 offset:1024
	ds_read_b128 v[176:179], v180 offset:2048
	ds_read_b128 v[180:183], v180 offset:3072
	s_add_u32 s52, s52, 0x80000
	s_addc_u32 s53, s53, 0
	s_mov_b32 m0, s59
	v_lshl_add_u64 v[224:225], s[52:53], 0, v[134:135]
	ds_read_b128 v[184:187], v155 offset:32768
	ds_read_b128 v[188:191], v155 offset:33792
	ds_read_b128 v[192:195], v155 offset:34816
	ds_read_b128 v[196:199], v155 offset:35840
	ds_read_b128 v[200:203], v155 offset:36864
	ds_read_b128 v[204:207], v155 offset:37888
	ds_read_b128 v[208:211], v155 offset:38912
	ds_read_b128 v[214:217], v155 offset:39936
	global_load_lds_dwordx4 v[224:225], off
	v_lshl_add_u64 v[224:225], s[52:53], 0, v[130:131]
	s_mov_b32 m0, s60
	s_nop 0
	global_load_lds_dwordx4 v[224:225], off
	s_waitcnt vmcnt(8)
	s_waitcnt lgkmcnt(0)
	s_barrier
	s_setprio 1
	s_waitcnt lgkmcnt(0)
	v_mfma_f32_16x16x32_bf16 v[124:127], v[144:147], v[184:187], v[124:127]
	v_mfma_f32_16x16x32_bf16 v[120:123], v[160:163], v[184:187], v[120:123]
	v_mfma_f32_16x16x32_bf16 v[108:111], v[144:147], v[192:195], v[108:111]
	v_mfma_f32_16x16x32_bf16 v[104:107], v[160:163], v[192:195], v[104:107]
	v_mfma_f32_16x16x32_bf16 v[92:95], v[144:147], v[200:203], v[92:95]
	v_mfma_f32_16x16x32_bf16 v[88:91], v[160:163], v[200:203], v[88:91]
	v_mfma_f32_16x16x32_bf16 v[76:79], v[144:147], v[208:211], v[76:79]
	v_mfma_f32_16x16x32_bf16 v[72:75], v[160:163], v[208:211], v[72:75]
	v_mfma_f32_16x16x32_bf16 v[124:127], v[156:159], v[188:191], v[124:127]
	v_mfma_f32_16x16x32_bf16 v[120:123], v[164:167], v[188:191], v[120:123]
	v_mfma_f32_16x16x32_bf16 v[108:111], v[156:159], v[196:199], v[108:111]
	v_mfma_f32_16x16x32_bf16 v[104:107], v[164:167], v[196:199], v[104:107]
	v_mfma_f32_16x16x32_bf16 v[92:95], v[156:159], v[204:207], v[92:95]
	v_mfma_f32_16x16x32_bf16 v[88:91], v[164:167], v[204:207], v[88:91]
	v_mfma_f32_16x16x32_bf16 v[76:79], v[156:159], v[214:217], v[76:79]
	v_mfma_f32_16x16x32_bf16 v[72:75], v[164:167], v[214:217], v[72:75]
	v_mfma_f32_16x16x32_bf16 v[116:119], v[168:171], v[184:187], v[116:119]
	v_mfma_f32_16x16x32_bf16 v[112:115], v[176:179], v[184:187], v[112:115]
	v_mfma_f32_16x16x32_bf16 v[100:103], v[168:171], v[192:195], v[100:103]
	v_mfma_f32_16x16x32_bf16 v[96:99], v[176:179], v[192:195], v[96:99]
	v_mfma_f32_16x16x32_bf16 v[84:87], v[168:171], v[200:203], v[84:87]
	v_mfma_f32_16x16x32_bf16 v[80:83], v[176:179], v[200:203], v[80:83]
	v_mfma_f32_16x16x32_bf16 v[68:71], v[168:171], v[208:211], v[68:71]
	v_mfma_f32_16x16x32_bf16 v[64:67], v[176:179], v[208:211], v[64:67]
	v_mfma_f32_16x16x32_bf16 v[116:119], v[172:175], v[188:191], v[116:119]
	v_mfma_f32_16x16x32_bf16 v[112:115], v[180:183], v[188:191], v[112:115]
	v_mfma_f32_16x16x32_bf16 v[100:103], v[172:175], v[196:199], v[100:103]
	v_mfma_f32_16x16x32_bf16 v[96:99], v[180:183], v[196:199], v[96:99]
	v_mfma_f32_16x16x32_bf16 v[84:87], v[172:175], v[204:207], v[84:87]
	v_mfma_f32_16x16x32_bf16 v[80:83], v[180:183], v[204:207], v[80:83]
	v_mfma_f32_16x16x32_bf16 v[68:71], v[172:175], v[214:217], v[68:71]
	v_mfma_f32_16x16x32_bf16 v[64:67], v[180:183], v[214:217], v[64:67]
	s_setprio 0
	s_barrier
	s_add_i32 s52, s74, s56
	v_lshl_add_u64 v[148:149], v[148:149], 0, s[16:17]
	s_mov_b32 m0, s52
	ds_read_b128 v[184:187], v155 offset:49152
	ds_read_b128 v[188:191], v155 offset:50176
	ds_read_b128 v[192:195], v155 offset:51200
	ds_read_b128 v[196:199], v155 offset:52224
	ds_read_b128 v[200:203], v155 offset:53248
	ds_read_b128 v[204:207], v155 offset:54272
	ds_read_b128 v[208:211], v155 offset:55296
	ds_read_b128 v[214:217], v155 offset:56320
	global_load_lds_dwordx4 v[148:149], off
	s_add_i32 m0, s52, 0x2000
	s_add_u32 s50, s50, 0x80080
	v_lshl_add_u64 v[148:149], v[218:219], 0, s[16:17]
	s_addc_u32 s51, s51, 0
	s_add_i32 s52, s75, s56
	global_load_lds_dwordx4 v[148:149], off
	v_lshl_add_u64 v[148:149], s[50:51], 0, v[132:133]
	s_mov_b32 m0, s52
	s_nop 0
	global_load_lds_dwordx4 v[148:149], off
	v_lshl_add_u64 v[148:149], s[50:51], 0, v[128:129]
	s_add_i32 m0, s52, 0x2000
	s_nop 0
	global_load_lds_dwordx4 v[148:149], off
	v_lshl_add_u64 v[148:149], v[220:221], 0, s[16:17]
	s_mov_b32 m0, s62
	s_nop 0
	global_load_lds_dwordx4 v[148:149], off
	v_lshl_add_u64 v[148:149], v[222:223], 0, s[16:17]
	s_mov_b32 m0, s63
	s_nop 0
	global_load_lds_dwordx4 v[148:149], off
	s_waitcnt vmcnt(8)
	s_waitcnt lgkmcnt(0)
	s_barrier
	s_setprio 1
	s_waitcnt lgkmcnt(0)
	v_mfma_f32_16x16x32_bf16 v[60:63], v[144:147], v[184:187], v[60:63]
	v_mfma_f32_16x16x32_bf16 v[56:59], v[160:163], v[184:187], v[56:59]
	v_mfma_f32_16x16x32_bf16 v[44:47], v[144:147], v[192:195], v[44:47]
	v_mfma_f32_16x16x32_bf16 v[40:43], v[160:163], v[192:195], v[40:43]
	v_mfma_f32_16x16x32_bf16 v[28:31], v[144:147], v[200:203], v[28:31]
	v_mfma_f32_16x16x32_bf16 v[24:27], v[160:163], v[200:203], v[24:27]
	v_mfma_f32_16x16x32_bf16 v[12:15], v[144:147], v[208:211], v[12:15]
	v_mfma_f32_16x16x32_bf16 v[8:11], v[160:163], v[208:211], v[8:11]
	v_mfma_f32_16x16x32_bf16 v[60:63], v[156:159], v[188:191], v[60:63]
	v_mfma_f32_16x16x32_bf16 v[56:59], v[164:167], v[188:191], v[56:59]
	v_mfma_f32_16x16x32_bf16 v[44:47], v[156:159], v[196:199], v[44:47]
	v_mfma_f32_16x16x32_bf16 v[40:43], v[164:167], v[196:199], v[40:43]
	v_mfma_f32_16x16x32_bf16 v[28:31], v[156:159], v[204:207], v[28:31]
	v_mfma_f32_16x16x32_bf16 v[24:27], v[164:167], v[204:207], v[24:27]
	v_mfma_f32_16x16x32_bf16 v[12:15], v[156:159], v[214:217], v[12:15]
	v_mfma_f32_16x16x32_bf16 v[8:11], v[164:167], v[214:217], v[8:11]
	v_mfma_f32_16x16x32_bf16 v[52:55], v[168:171], v[184:187], v[52:55]
	v_mfma_f32_16x16x32_bf16 v[48:51], v[176:179], v[184:187], v[48:51]
	v_mfma_f32_16x16x32_bf16 v[36:39], v[168:171], v[192:195], v[36:39]
	v_mfma_f32_16x16x32_bf16 v[32:35], v[176:179], v[192:195], v[32:35]
	v_mfma_f32_16x16x32_bf16 v[20:23], v[168:171], v[200:203], v[20:23]
	v_mfma_f32_16x16x32_bf16 v[16:19], v[176:179], v[200:203], v[16:19]
	v_mfma_f32_16x16x32_bf16 v[4:7], v[168:171], v[208:211], v[4:7]
	v_mfma_f32_16x16x32_bf16 v[0:3], v[176:179], v[208:211], v[0:3]
	v_mfma_f32_16x16x32_bf16 v[52:55], v[172:175], v[188:191], v[52:55]
	v_mfma_f32_16x16x32_bf16 v[48:51], v[180:183], v[188:191], v[48:51]
	v_mfma_f32_16x16x32_bf16 v[36:39], v[172:175], v[196:199], v[36:39]
	v_mfma_f32_16x16x32_bf16 v[32:35], v[180:183], v[196:199], v[32:35]
	v_mfma_f32_16x16x32_bf16 v[20:23], v[172:175], v[204:207], v[20:23]
	v_mfma_f32_16x16x32_bf16 v[16:19], v[180:183], v[204:207], v[16:19]
	v_mfma_f32_16x16x32_bf16 v[4:7], v[172:175], v[214:217], v[4:7]
	v_mfma_f32_16x16x32_bf16 v[0:3], v[180:183], v[214:217], v[0:3]
	s_setprio 0
	s_barrier
	s_add_i32 s73, s73, 2
	s_add_u32 s48, s48, 0x100
	s_addc_u32 s49, s49, 0
	s_add_u32 s71, s71, 0x100
	s_addc_u32 s72, s72, 0
	s_cmp_gt_u32 s73, 29
	s_cbranch_scc0 .LBB0_1241
	s_and_b64 vcc, exec, s[18:19]
	s_cbranch_vccz .LBB0_1244
	s_barrier

.LBB0_2180:
	ds_read_b128 v[144:147], v153
	ds_read_b128 v[156:159], v153 offset:1024
	ds_read_b128 v[160:163], v153 offset:2048
	ds_read_b128 v[164:167], v153 offset:3072
	ds_read_b128 v[168:171], v154
	ds_read_b128 v[172:175], v154 offset:1024
	ds_read_b128 v[176:179], v154 offset:2048
	ds_read_b128 v[180:183], v154 offset:3072
	s_add_u32 s42, s40, 0xfff80080
	s_addc_u32 s43, s41, -1
	s_cmp_eq_u32 s63, 28
	s_cselect_b32 s45, s29, s43
	s_cselect_b32 s44, s59, s42
	s_cselect_b32 s43, s27, s62
	s_cselect_b32 s42, s60, s61
	v_lshl_add_u64 v[148:149], s[40:41], 0, v[136:137]
	s_add_i32 m0, s39, 0xc000
	ds_read_b128 v[184:187], v155
	ds_read_b128 v[188:191], v155 offset:1024
	ds_read_b128 v[192:195], v155 offset:2048
	ds_read_b128 v[196:199], v155 offset:3072
	ds_read_b128 v[200:203], v155 offset:4096
	ds_read_b128 v[204:207], v155 offset:5120
	ds_read_b128 v[208:211], v155 offset:6144
	ds_read_b128 v[212:215], v155 offset:7168
	global_load_lds_dwordx4 v[148:149], off
	v_lshl_add_u64 v[148:149], s[40:41], 0, v[138:139]
	s_add_i32 m0, s39, 0xe000
	s_nop 0
	global_load_lds_dwordx4 v[148:149], off
	s_waitcnt vmcnt(8)
	s_waitcnt lgkmcnt(0)
	s_barrier
	s_setprio 1
	s_waitcnt lgkmcnt(0)
	v_mfma_f32_16x16x32_bf16 v[120:123], v[144:147], v[184:187], v[120:123]
	v_mfma_f32_16x16x32_bf16 v[124:127], v[160:163], v[184:187], v[124:127]
	v_mfma_f32_16x16x32_bf16 v[104:107], v[144:147], v[192:195], v[104:107]
	v_mfma_f32_16x16x32_bf16 v[108:111], v[160:163], v[192:195], v[108:111]
	v_mfma_f32_16x16x32_bf16 v[88:91], v[144:147], v[200:203], v[88:91]
	v_mfma_f32_16x16x32_bf16 v[92:95], v[160:163], v[200:203], v[92:95]
	v_mfma_f32_16x16x32_bf16 v[72:75], v[144:147], v[208:211], v[72:75]
	v_mfma_f32_16x16x32_bf16 v[76:79], v[160:163], v[208:211], v[76:79]
	v_mfma_f32_16x16x32_bf16 v[120:123], v[156:159], v[188:191], v[120:123]
	v_mfma_f32_16x16x32_bf16 v[124:127], v[164:167], v[188:191], v[124:127]
	v_mfma_f32_16x16x32_bf16 v[104:107], v[156:159], v[196:199], v[104:107]
	v_mfma_f32_16x16x32_bf16 v[108:111], v[164:167], v[196:199], v[108:111]
	v_mfma_f32_16x16x32_bf16 v[88:91], v[156:159], v[204:207], v[88:91]
	v_mfma_f32_16x16x32_bf16 v[92:95], v[164:167], v[204:207], v[92:95]
	v_mfma_f32_16x16x32_bf16 v[72:75], v[156:159], v[212:215], v[72:75]
	v_mfma_f32_16x16x32_bf16 v[76:79], v[164:167], v[212:215], v[76:79]
	v_mfma_f32_16x16x32_bf16 v[112:115], v[168:171], v[184:187], v[112:115]
	v_mfma_f32_16x16x32_bf16 v[116:119], v[176:179], v[184:187], v[116:119]
	v_mfma_f32_16x16x32_bf16 v[96:99], v[168:171], v[192:195], v[96:99]
	v_mfma_f32_16x16x32_bf16 v[100:103], v[176:179], v[192:195], v[100:103]
	v_mfma_f32_16x16x32_bf16 v[80:83], v[168:171], v[200:203], v[80:83]
	v_mfma_f32_16x16x32_bf16 v[84:87], v[176:179], v[200:203], v[84:87]
	v_mfma_f32_16x16x32_bf16 v[64:67], v[168:171], v[208:211], v[64:67]
	v_mfma_f32_16x16x32_bf16 v[68:71], v[176:179], v[208:211], v[68:71]
	v_mfma_f32_16x16x32_bf16 v[112:115], v[172:175], v[188:191], v[112:115]
	v_mfma_f32_16x16x32_bf16 v[116:119], v[180:183], v[188:191], v[116:119]
	v_mfma_f32_16x16x32_bf16 v[96:99], v[172:175], v[196:199], v[96:99]
	v_mfma_f32_16x16x32_bf16 v[100:103], v[180:183], v[196:199], v[100:103]
	v_mfma_f32_16x16x32_bf16 v[80:83], v[172:175], v[204:207], v[80:83]
	v_mfma_f32_16x16x32_bf16 v[84:87], v[180:183], v[204:207], v[84:87]
	v_mfma_f32_16x16x32_bf16 v[64:67], v[172:175], v[212:215], v[64:67]
	v_mfma_f32_16x16x32_bf16 v[68:71], v[180:183], v[212:215], v[68:71]
	s_setprio 0
	s_barrier
	s_add_i32 s64, s56, s47
	v_lshl_add_u64 v[148:149], s[42:43], 0, v[132:133]
	s_mov_b32 m0, s64
	ds_read_b128 v[184:187], v155 offset:16384
	ds_read_b128 v[188:191], v155 offset:17408
	ds_read_b128 v[192:195], v155 offset:18432
	ds_read_b128 v[196:199], v155 offset:19456
	ds_read_b128 v[200:203], v155 offset:20480
	ds_read_b128 v[204:207], v155 offset:21504
	ds_read_b128 v[208:211], v155 offset:22528
	ds_read_b128 v[212:215], v155 offset:23552
	global_load_lds_dwordx4 v[148:149], off
	s_add_i32 m0, s64, 0x2000
	s_add_u32 s64, s42, 0x80000
	v_lshl_add_u64 v[216:217], s[42:43], 0, v[128:129]
	s_addc_u32 s65, s43, 0
	s_add_i32 s66, s57, s47
	global_load_lds_dwordx4 v[216:217], off
	v_lshl_add_u64 v[218:219], s[64:65], 0, v[132:133]
	s_mov_b32 m0, s66
	v_lshl_add_u64 v[220:221], s[44:45], 0, v[130:131]
	global_load_lds_dwordx4 v[218:219], off
	v_lshl_add_u64 v[218:219], s[64:65], 0, v[128:129]
	s_add_i32 m0, s66, 0x2000
	s_nop 0
	global_load_lds_dwordx4 v[218:219], off
	v_lshl_add_u64 v[218:219], s[44:45], 0, v[134:135]
	s_mov_b32 m0, s39
	s_nop 0
	global_load_lds_dwordx4 v[218:219], off
	s_mov_b32 m0, s49
	s_nop 0
	global_load_lds_dwordx4 v[220:221], off
	s_waitcnt vmcnt(8)
	s_waitcnt lgkmcnt(0)
	s_barrier
	s_setprio 1
	s_waitcnt lgkmcnt(0)
	v_mfma_f32_16x16x32_bf16 v[56:59], v[144:147], v[184:187], v[56:59]
	v_mfma_f32_16x16x32_bf16 v[60:63], v[160:163], v[184:187], v[60:63]
	v_mfma_f32_16x16x32_bf16 v[40:43], v[144:147], v[192:195], v[40:43]
	v_mfma_f32_16x16x32_bf16 v[44:47], v[160:163], v[192:195], v[44:47]
	v_mfma_f32_16x16x32_bf16 v[24:27], v[144:147], v[200:203], v[24:27]
	v_mfma_f32_16x16x32_bf16 v[28:31], v[160:163], v[200:203], v[28:31]
	v_mfma_f32_16x16x32_bf16 v[8:11], v[144:147], v[208:211], v[8:11]
	v_mfma_f32_16x16x32_bf16 v[12:15], v[160:163], v[208:211], v[12:15]
	v_mfma_f32_16x16x32_bf16 v[56:59], v[156:159], v[188:191], v[56:59]
	v_mfma_f32_16x16x32_bf16 v[60:63], v[164:167], v[188:191], v[60:63]
	v_mfma_f32_16x16x32_bf16 v[40:43], v[156:159], v[196:199], v[40:43]
	v_mfma_f32_16x16x32_bf16 v[44:47], v[164:167], v[196:199], v[44:47]
	v_mfma_f32_16x16x32_bf16 v[24:27], v[156:159], v[204:207], v[24:27]
	v_mfma_f32_16x16x32_bf16 v[28:31], v[164:167], v[204:207], v[28:31]
	v_mfma_f32_16x16x32_bf16 v[8:11], v[156:159], v[212:215], v[8:11]
	v_mfma_f32_16x16x32_bf16 v[12:15], v[164:167], v[212:215], v[12:15]
	v_mfma_f32_16x16x32_bf16 v[48:51], v[168:171], v[184:187], v[48:51]
	v_mfma_f32_16x16x32_bf16 v[52:55], v[176:179], v[184:187], v[52:55]
	v_mfma_f32_16x16x32_bf16 v[32:35], v[168:171], v[192:195], v[32:35]
	v_mfma_f32_16x16x32_bf16 v[36:39], v[176:179], v[192:195], v[36:39]
	v_mfma_f32_16x16x32_bf16 v[16:19], v[168:171], v[200:203], v[16:19]
	v_mfma_f32_16x16x32_bf16 v[20:23], v[176:179], v[200:203], v[20:23]
	v_mfma_f32_16x16x32_bf16 v[0:3], v[168:171], v[208:211], v[0:3]
	v_mfma_f32_16x16x32_bf16 v[4:7], v[176:179], v[208:211], v[4:7]
	v_mfma_f32_16x16x32_bf16 v[48:51], v[172:175], v[188:191], v[48:51]
	v_mfma_f32_16x16x32_bf16 v[52:55], v[180:183], v[188:191], v[52:55]
	v_mfma_f32_16x16x32_bf16 v[32:35], v[172:175], v[196:199], v[32:35]
	v_mfma_f32_16x16x32_bf16 v[36:39], v[180:183], v[196:199], v[36:39]
	v_mfma_f32_16x16x32_bf16 v[16:19], v[172:175], v[204:207], v[16:19]
	v_mfma_f32_16x16x32_bf16 v[20:23], v[180:183], v[204:207], v[20:23]
	v_mfma_f32_16x16x32_bf16 v[0:3], v[172:175], v[212:215], v[0:3]
	v_mfma_f32_16x16x32_bf16 v[4:7], v[180:183], v[212:215], v[4:7]
	s_setprio 0
	s_barrier
	s_add_i32 s64, 0, 0x18000
	s_add_i32 s65, 0, 0x1c000
	v_add_u32_e32 v164, s64, v151
	v_add_u32_e32 v180, s65, v151
	ds_read_b128 v[144:147], v164
	ds_read_b128 v[156:159], v164 offset:1024
	ds_read_b128 v[160:163], v164 offset:2048
	ds_read_b128 v[164:167], v164 offset:3072
	ds_read_b128 v[168:171], v180
	ds_read_b128 v[172:175], v180 offset:1024
	ds_read_b128 v[176:179], v180 offset:2048
	ds_read_b128 v[180:183], v180 offset:3072
	s_add_u32 s44, s44, 0x80000
	s_addc_u32 s45, s45, 0
	s_mov_b32 m0, s50
	v_lshl_add_u64 v[222:223], s[44:45], 0, v[134:135]
	ds_read_b128 v[184:187], v155 offset:32768
	ds_read_b128 v[188:191], v155 offset:33792
	ds_read_b128 v[192:195], v155 offset:34816
	ds_read_b128 v[196:199], v155 offset:35840
	ds_read_b128 v[200:203], v155 offset:36864
	ds_read_b128 v[204:207], v155 offset:37888
	ds_read_b128 v[208:211], v155 offset:38912
	ds_read_b128 v[212:215], v155 offset:39936
	global_load_lds_dwordx4 v[222:223], off
	v_lshl_add_u64 v[222:223], s[44:45], 0, v[130:131]
	s_mov_b32 m0, s51
	s_nop 0
	global_load_lds_dwordx4 v[222:223], off
	s_waitcnt vmcnt(8)
	s_waitcnt lgkmcnt(0)
	s_barrier
	s_setprio 1
	s_waitcnt lgkmcnt(0)
	v_mfma_f32_16x16x32_bf16 v[120:123], v[144:147], v[184:187], v[120:123]
	v_mfma_f32_16x16x32_bf16 v[124:127], v[160:163], v[184:187], v[124:127]
	v_mfma_f32_16x16x32_bf16 v[104:107], v[144:147], v[192:195], v[104:107]
	v_mfma_f32_16x16x32_bf16 v[108:111], v[160:163], v[192:195], v[108:111]
	v_mfma_f32_16x16x32_bf16 v[88:91], v[144:147], v[200:203], v[88:91]
	v_mfma_f32_16x16x32_bf16 v[92:95], v[160:163], v[200:203], v[92:95]
	v_mfma_f32_16x16x32_bf16 v[72:75], v[144:147], v[208:211], v[72:75]
	v_mfma_f32_16x16x32_bf16 v[76:79], v[160:163], v[208:211], v[76:79]
	v_mfma_f32_16x16x32_bf16 v[120:123], v[156:159], v[188:191], v[120:123]
	v_mfma_f32_16x16x32_bf16 v[124:127], v[164:167], v[188:191], v[124:127]
	v_mfma_f32_16x16x32_bf16 v[104:107], v[156:159], v[196:199], v[104:107]
	v_mfma_f32_16x16x32_bf16 v[108:111], v[164:167], v[196:199], v[108:111]
	v_mfma_f32_16x16x32_bf16 v[88:91], v[156:159], v[204:207], v[88:91]
	v_mfma_f32_16x16x32_bf16 v[92:95], v[164:167], v[204:207], v[92:95]
	v_mfma_f32_16x16x32_bf16 v[72:75], v[156:159], v[212:215], v[72:75]
	v_mfma_f32_16x16x32_bf16 v[76:79], v[164:167], v[212:215], v[76:79]
	v_mfma_f32_16x16x32_bf16 v[112:115], v[168:171], v[184:187], v[112:115]
	v_mfma_f32_16x16x32_bf16 v[116:119], v[176:179], v[184:187], v[116:119]
	v_mfma_f32_16x16x32_bf16 v[96:99], v[168:171], v[192:195], v[96:99]
	v_mfma_f32_16x16x32_bf16 v[100:103], v[176:179], v[192:195], v[100:103]
	v_mfma_f32_16x16x32_bf16 v[80:83], v[168:171], v[200:203], v[80:83]
	v_mfma_f32_16x16x32_bf16 v[84:87], v[176:179], v[200:203], v[84:87]
	v_mfma_f32_16x16x32_bf16 v[64:67], v[168:171], v[208:211], v[64:67]
	v_mfma_f32_16x16x32_bf16 v[68:71], v[176:179], v[208:211], v[68:71]
	v_mfma_f32_16x16x32_bf16 v[112:115], v[172:175], v[188:191], v[112:115]
	v_mfma_f32_16x16x32_bf16 v[116:119], v[180:183], v[188:191], v[116:119]
	v_mfma_f32_16x16x32_bf16 v[96:99], v[172:175], v[196:199], v[96:99]
	v_mfma_f32_16x16x32_bf16 v[100:103], v[180:183], v[196:199], v[100:103]
	v_mfma_f32_16x16x32_bf16 v[80:83], v[172:175], v[204:207], v[80:83]
	v_mfma_f32_16x16x32_bf16 v[84:87], v[180:183], v[204:207], v[84:87]
	v_mfma_f32_16x16x32_bf16 v[64:67], v[172:175], v[212:215], v[64:67]
	v_mfma_f32_16x16x32_bf16 v[68:71], v[180:183], v[212:215], v[68:71]
	s_setprio 0
	s_barrier
	s_add_i32 s44, s64, s47
	v_lshl_add_u64 v[148:149], v[148:149], 0, s[12:13]
	s_mov_b32 m0, s44
	ds_read_b128 v[184:187], v155 offset:49152
	ds_read_b128 v[188:191], v155 offset:50176
	ds_read_b128 v[192:195], v155 offset:51200
	ds_read_b128 v[196:199], v155 offset:52224
	ds_read_b128 v[200:203], v155 offset:53248
	ds_read_b128 v[204:207], v155 offset:54272
	ds_read_b128 v[208:211], v155 offset:55296
	ds_read_b128 v[212:215], v155 offset:56320
	global_load_lds_dwordx4 v[148:149], off
	s_add_i32 m0, s44, 0x2000
	s_add_u32 s42, s42, 0x80080
	v_lshl_add_u64 v[148:149], v[216:217], 0, s[12:13]
	s_addc_u32 s43, s43, 0
	s_add_i32 s44, s65, s47
	global_load_lds_dwordx4 v[148:149], off
	v_lshl_add_u64 v[148:149], s[42:43], 0, v[132:133]
	s_mov_b32 m0, s44
	s_nop 0
	global_load_lds_dwordx4 v[148:149], off
	v_lshl_add_u64 v[148:149], s[42:43], 0, v[128:129]
	s_add_i32 m0, s44, 0x2000
	s_nop 0
	global_load_lds_dwordx4 v[148:149], off
	v_lshl_add_u64 v[148:149], v[218:219], 0, s[12:13]
	s_mov_b32 m0, s53
	s_nop 0
	global_load_lds_dwordx4 v[148:149], off
	v_lshl_add_u64 v[148:149], v[220:221], 0, s[12:13]
	s_mov_b32 m0, s54
	s_nop 0
	global_load_lds_dwordx4 v[148:149], off
	s_waitcnt vmcnt(8)
	s_waitcnt lgkmcnt(0)
	s_barrier
	s_setprio 1
	s_waitcnt lgkmcnt(0)
	v_mfma_f32_16x16x32_bf16 v[56:59], v[144:147], v[184:187], v[56:59]
	v_mfma_f32_16x16x32_bf16 v[60:63], v[160:163], v[184:187], v[60:63]
	v_mfma_f32_16x16x32_bf16 v[40:43], v[144:147], v[192:195], v[40:43]
	v_mfma_f32_16x16x32_bf16 v[44:47], v[160:163], v[192:195], v[44:47]
	v_mfma_f32_16x16x32_bf16 v[24:27], v[144:147], v[200:203], v[24:27]
	v_mfma_f32_16x16x32_bf16 v[28:31], v[160:163], v[200:203], v[28:31]
	v_mfma_f32_16x16x32_bf16 v[8:11], v[144:147], v[208:211], v[8:11]
	v_mfma_f32_16x16x32_bf16 v[12:15], v[160:163], v[208:211], v[12:15]
	v_mfma_f32_16x16x32_bf16 v[56:59], v[156:159], v[188:191], v[56:59]
	v_mfma_f32_16x16x32_bf16 v[60:63], v[164:167], v[188:191], v[60:63]
	v_mfma_f32_16x16x32_bf16 v[40:43], v[156:159], v[196:199], v[40:43]
	v_mfma_f32_16x16x32_bf16 v[44:47], v[164:167], v[196:199], v[44:47]
	v_mfma_f32_16x16x32_bf16 v[24:27], v[156:159], v[204:207], v[24:27]
	v_mfma_f32_16x16x32_bf16 v[28:31], v[164:167], v[204:207], v[28:31]
	v_mfma_f32_16x16x32_bf16 v[8:11], v[156:159], v[212:215], v[8:11]
	v_mfma_f32_16x16x32_bf16 v[12:15], v[164:167], v[212:215], v[12:15]
	v_mfma_f32_16x16x32_bf16 v[48:51], v[168:171], v[184:187], v[48:51]
	v_mfma_f32_16x16x32_bf16 v[52:55], v[176:179], v[184:187], v[52:55]
	v_mfma_f32_16x16x32_bf16 v[32:35], v[168:171], v[192:195], v[32:35]
	v_mfma_f32_16x16x32_bf16 v[36:39], v[176:179], v[192:195], v[36:39]
	v_mfma_f32_16x16x32_bf16 v[16:19], v[168:171], v[200:203], v[16:19]
	v_mfma_f32_16x16x32_bf16 v[20:23], v[176:179], v[200:203], v[20:23]
	v_mfma_f32_16x16x32_bf16 v[0:3], v[168:171], v[208:211], v[0:3]
	v_mfma_f32_16x16x32_bf16 v[4:7], v[176:179], v[208:211], v[4:7]
	v_mfma_f32_16x16x32_bf16 v[48:51], v[172:175], v[188:191], v[48:51]
	v_mfma_f32_16x16x32_bf16 v[52:55], v[180:183], v[188:191], v[52:55]
	v_mfma_f32_16x16x32_bf16 v[32:35], v[172:175], v[196:199], v[32:35]
	v_mfma_f32_16x16x32_bf16 v[36:39], v[180:183], v[196:199], v[36:39]
	v_mfma_f32_16x16x32_bf16 v[16:19], v[172:175], v[204:207], v[16:19]
	v_mfma_f32_16x16x32_bf16 v[20:23], v[180:183], v[204:207], v[20:23]
	v_mfma_f32_16x16x32_bf16 v[0:3], v[172:175], v[212:215], v[0:3]
	v_mfma_f32_16x16x32_bf16 v[4:7], v[180:183], v[212:215], v[4:7]
	s_setprio 0
	s_barrier
	s_add_i32 s63, s63, 2
	s_add_u32 s40, s40, 0x100
	s_addc_u32 s41, s41, 0
	s_add_u32 s61, s61, 0x100
	s_addc_u32 s62, s62, 0
	s_cmp_gt_u32 s63, 29
	s_cbranch_scc0 .LBB0_2180
	s_and_b64 vcc, exec, s[14:15]
	s_cbranch_vccnz .LBB0_2184
	s_andn2_b64 vcc, exec, s[16:17]
	s_cbranch_vccz .LBB0_2185
